# no cg grid.sync at start (census wait), p3 carry-in loads issued together, final RMSNorm row loop software-pipelined
# speedup vs baseline: 1.0611x; 1.0053x over previous
; __device__ __forceinline__ unsigned xb_ld(unsigned* p)              { return __hip_atomic_load(p, __ATOMIC_RELAXED, __HIP_MEMORY_SCOPE_AGENT); }
; __device__ __forceinline__ unsigned xb_add(unsigned* p, unsigned v) { return __hip_atomic_fetch_add(p, v, __ATOMIC_RELAXED, __HIP_MEMORY_SCOPE_AGENT); }
; __device__ __forceinline__ unsigned xb_xcc_id() { return (unsigned)__builtin_amdgcn_s_getreg((3 << 11) | 20) & 0xFu; }
; __global__ void __launch_bounds__(NTHREADS, 2) hymba_fwd(Args a) {
;     ...
;     if (threadIdx.x == 0) { const unsigned x = xb_xcc_id(); misc[2] = xb_add(&bar0[XB_XCNT(x)], 1u); misc[3] = x; }
;     grid.sync();
;     if (threadIdx.x == 0) {
;         unsigned ok = ((unsigned)G % 8u == 0u) ? 1u : 0u;
; #pragma unroll
;         for (unsigned j = 0; j < 16; ++j) { const unsigned c = xb_ld(&bar0[XB_XCNT(j)]); ok &= (j < 8u) ? (c == (unsigned)G / 8u ? 1u : 0u) : (c == 0u ? 1u : 0u); }
;         misc[4] = ok ? (misc[2] * 8u + misc[3]) : (unsigned)blockIdx.x;
;     }
;     __syncthreads();
;     const int bid = (int)misc[4];
.LBB0_6:
	s_or_b64 exec, exec, s[8:9]
	v_lshrrev_b32_e32 v1, 20, v0
	v_lshrrev_b32_e32 v0, 10, v0
	v_or_b32_e32 v0, v0, v1
	s_movk_i32 s3, 0x3ff
	v_and_or_b32 v0, v0, s3, v209
	v_cmp_eq_u32_e32 vcc, 0, v0
	s_waitcnt lgkmcnt(0)
	s_barrier
	s_and_saveexec_b64 s[22:23], s[10:11]
	s_cbranch_execz .LBB0_20
.Lcensus_retry:
	v_mov_b32_e32 v0, 0x1d800000
	global_load_dword v1, v0, s[4:5] offset:1024 sc1
	global_load_dword v2, v0, s[4:5] offset:1280 sc1
	global_load_dword v3, v0, s[4:5] offset:1536 sc1
	global_load_dword v4, v0, s[4:5] offset:1792 sc1
	global_load_dword v5, v0, s[4:5] offset:2048 sc1
	global_load_dword v6, v0, s[4:5] offset:2304 sc1
	global_load_dword v7, v0, s[4:5] offset:2560 sc1
	global_load_dword v8, v0, s[4:5] offset:2816 sc1
	global_load_dword v9, v0, s[4:5] offset:3072 sc1
	global_load_dword v10, v0, s[4:5] offset:3328 sc1
	global_load_dword v11, v0, s[4:5] offset:3584 sc1
	global_load_dword v12, v0, s[4:5] offset:3840 sc1
	v_mov_b32_e32 v0, 0x1d801000
	global_load_dword v13, v0, s[4:5] sc1
	global_load_dword v14, v0, s[4:5] offset:256 sc1
	global_load_dword v15, v0, s[4:5] offset:512 sc1
	global_load_dword v16, v0, s[4:5] offset:768 sc1
	s_waitcnt vmcnt(0)
	v_add_u32_e32 v17, v1, v2
	v_add_u32_e32 v17, v17, v3
	v_add_u32_e32 v17, v17, v4
	v_add_u32_e32 v17, v17, v5
	v_add_u32_e32 v17, v17, v6
	v_add_u32_e32 v17, v17, v7
	v_add_u32_e32 v17, v17, v8
	v_add_u32_e32 v17, v17, v9
	v_add_u32_e32 v17, v17, v10
	v_add_u32_e32 v17, v17, v11
	v_add_u32_e32 v17, v17, v12
	v_add_u32_e32 v17, v17, v13
	v_add_u32_e32 v17, v17, v14
	v_add_u32_e32 v17, v17, v15
	v_add_u32_e32 v17, v17, v16
	v_cmp_ne_u32_e32 vcc, s20, v17
	s_cbranch_vccz .Lcensus_ok
	s_sleep 1
	s_branch .Lcensus_retry
.Lcensus_ok:
	s_and_b32 s3, s20, 7
	s_cmp_eq_u32 s3, 0
	s_cselect_b64 s[24:25], -1, 0
	s_lshr_b32 s3, s20, 3
	s_waitcnt vmcnt(15)
	v_cmp_eq_u32_e32 vcc, s3, v1
	s_and_b64 s[24:25], vcc, s[24:25]
	s_waitcnt vmcnt(13)
	v_cmp_eq_u32_e64 s[6:7], s3, v3
	s_waitcnt vmcnt(12)
	v_cmp_eq_u32_e64 s[8:9], s3, v4
	s_waitcnt vmcnt(11)
	v_cmp_eq_u32_e64 s[12:13], s3, v5
	s_waitcnt vmcnt(10)
	v_cmp_eq_u32_e64 s[14:15], s3, v6
	s_waitcnt vmcnt(9)
	v_cmp_eq_u32_e64 s[16:17], s3, v7
	s_waitcnt vmcnt(8)
	v_cmp_eq_u32_e64 s[18:19], s3, v8
	v_cmp_eq_u32_e64 s[4:5], s3, v2
	s_waitcnt vmcnt(0)
	v_or_b32_e32 v0, v16, v15
	v_or_b32_e32 v0, v0, v14
	v_or_b32_e32 v0, v0, v13
	v_or_b32_e32 v0, v0, v12
	v_or_b32_e32 v0, v0, v11
	v_or_b32_e32 v0, v0, v10
	v_or_b32_e32 v0, v0, v9
	v_cmp_eq_u32_e32 vcc, 0, v0
	s_and_b64 s[18:19], vcc, s[18:19]
	s_and_b64 s[16:17], s[18:19], s[16:17]
	s_and_b64 s[14:15], s[16:17], s[14:15]
	s_and_b64 s[12:13], s[14:15], s[12:13]
	s_and_b64 s[8:9], s[12:13], s[8:9]
	s_and_b64 s[6:7], s[8:9], s[6:7]
	s_and_b64 s[4:5], s[6:7], s[4:5]
	s_and_b64 s[4:5], s[4:5], s[24:25]
	s_andn2_b64 vcc, exec, s[4:5]
	v_mov_b32_e32 v0, s2
	s_cbranch_vccnz .LBB0_19
	v_mov_b32_e32 v2, 0x23fd4
	v_mov_b32_e32 v3, 1
	ds_write_b32 v2, v3
	s_add_i32 s2, 0, 0x23fc8
	v_mov_b32_e32 v0, s2
	s_add_i32 s2, 0, 0x23fcc
	ds_read_b32 v0, v0
	v_mov_b32_e32 v1, s2
	ds_read_b32 v1, v1
	s_waitcnt lgkmcnt(1)
	v_lshlrev_b32_e32 v0, 3, v0
	s_waitcnt lgkmcnt(0)
	v_add_u32_e32 v0, v0, v1

; #define WSPTR() kptr(224)
; __device__ __forceinline__ void ssm_p3(const Args& a, LAS unsigned char* lds, int layer, int G, int vb) {
;     ...
;         const int wt = wg * 8 + wave, b = wg & 7, g = ((wg >> 3) & 3) * 8 + wave, seg = wg >> 5;
;         const int rowbase = b * SEQ + seg * 512;
;         f32x4* ysc = (f32x4*)(WSPTR() + WS_YSCR) + (size_t)wt * (16 * 2 * 64);
;         {
;             const int cb = (layer * 2 + 1) * 32 + g;
;             const f32x2 ab = AB[cb * 64 + lane], ap = AP[cb * 64 + lane];
;             const f32x2* se = SE + ((size_t)((b * 32 + g) * 2 + 1) * 8) * 64 + lane;
;             float sr = 0.f, si = 0.f;
;             for (int k = 7; k > seg && !DIAG_NOCARRY; --k) { const f32x2 e = se[k * 64]; const float nr = ap[0] * sr - ap[1] * si + e[0], ni = ap[0] * si + ap[1] * sr + e[1]; sr = nr; si = ni; }
.LBB0_505:
	s_and_b32 s55, s39, 7
	s_bfe_u32 s59, s58, 0x20003
	s_lshl_b32 s26, s55, 6
	s_add_i32 s26, s23, s26
	s_lshl_b32 s27, s59, 4
	s_add_i32 s26, s26, s27
	s_ashr_i32 s27, s26, 31
	s_lshl_b64 s[80:81], s[26:27], 12
	s_and_b32 s27, s58, 24
	s_movk_i32 s28, 0xe0
	s_add_i32 s27, s27, s22
	s_ashr_i32 s26, s58, 5
	s_ashr_i32 s29, s28, 31
	s_add_u32 s36, s0, s28
	s_addc_u32 s37, s1, s29
	s_add_i32 s54, s27, s19
	v_lshl_or_b32 v2, s54, 6, v110
	v_ashrrev_i32_e32 v3, 31, v2
	v_lshl_add_u64 v[4:5], v[2:3], 3, s[8:9]
	global_load_dwordx2 v[102:103], v[4:5], off
	s_cmp_gt_i32 s26, 6
	s_cbranch_scc1 .LBB0_508
	v_lshl_add_u64 v[2:3], v[2:3], 3, s[76:77]
	global_load_dwordx2 v[2:3], v[2:3], off
	v_lshl_add_u64 v[4:5], v[114:115], 0, s[80:81]
	s_movk_i32 s28, 0xfe00
	s_mov_b32 s29, -1
	global_load_dwordx2 v[226:227], v[4:5], off
	v_lshl_add_u64 v[4:5], v[4:5], 0, s[28:29]
	global_load_dwordx2 v[228:229], v[4:5], off
	v_lshl_add_u64 v[4:5], v[4:5], 0, s[28:29]
	global_load_dwordx2 v[230:231], v[4:5], off
	v_lshl_add_u64 v[4:5], v[4:5], 0, s[28:29]
	global_load_dwordx2 v[232:233], v[4:5], off
	v_lshl_add_u64 v[4:5], v[4:5], 0, s[28:29]
	global_load_dwordx2 v[234:235], v[4:5], off
	v_lshl_add_u64 v[4:5], v[4:5], 0, s[28:29]
	global_load_dwordx2 v[236:237], v[4:5], off
	v_lshl_add_u64 v[4:5], v[4:5], 0, s[28:29]
	global_load_dwordx2 v[238:239], v[4:5], off
	v_mov_b32_e32 v132, 0
	v_mov_b32_e32 v133, 0
	s_mov_b32 s60, 7
	s_waitcnt vmcnt(6)
	v_mul_f32_e32 v240, v3, v133
	v_mul_f32_e32 v241, v2, v133
	v_fma_f32 v240, v2, v132, -v240
	v_fma_f32 v241, v3, v132, v241
	v_add_f32_e32 v132, v240, v226
	v_add_f32_e32 v133, v241, v227
	s_add_i32 s60, s60, -1
	s_cmp_le_i32 s60, s26
	s_cbranch_scc1 .LBB0_509
	s_waitcnt vmcnt(5)
	v_mul_f32_e32 v240, v3, v133
	v_mul_f32_e32 v241, v2, v133
	v_fma_f32 v240, v2, v132, -v240
	v_fma_f32 v241, v3, v132, v241
	v_add_f32_e32 v132, v240, v228
	v_add_f32_e32 v133, v241, v229
	s_add_i32 s60, s60, -1
	s_cmp_le_i32 s60, s26
	s_cbranch_scc1 .LBB0_509
	s_waitcnt vmcnt(4)
	v_mul_f32_e32 v240, v3, v133
	v_mul_f32_e32 v241, v2, v133
	v_fma_f32 v240, v2, v132, -v240
	v_fma_f32 v241, v3, v132, v241
	v_add_f32_e32 v132, v240, v230
	v_add_f32_e32 v133, v241, v231
	s_add_i32 s60, s60, -1
	s_cmp_le_i32 s60, s26
	s_cbranch_scc1 .LBB0_509
	s_waitcnt vmcnt(3)
	v_mul_f32_e32 v240, v3, v133
	v_mul_f32_e32 v241, v2, v133
	v_fma_f32 v240, v2, v132, -v240
	v_fma_f32 v241, v3, v132, v241
	v_add_f32_e32 v132, v240, v232
	v_add_f32_e32 v133, v241, v233
	s_add_i32 s60, s60, -1
	s_cmp_le_i32 s60, s26
	s_cbranch_scc1 .LBB0_509
	s_waitcnt vmcnt(2)
	v_mul_f32_e32 v240, v3, v133
	v_mul_f32_e32 v241, v2, v133
	v_fma_f32 v240, v2, v132, -v240
	v_fma_f32 v241, v3, v132, v241
	v_add_f32_e32 v132, v240, v234
	v_add_f32_e32 v133, v241, v235
	s_add_i32 s60, s60, -1
	s_cmp_le_i32 s60, s26
	s_cbranch_scc1 .LBB0_509
	s_waitcnt vmcnt(1)
	v_mul_f32_e32 v240, v3, v133
	v_mul_f32_e32 v241, v2, v133
	v_fma_f32 v240, v2, v132, -v240
	v_fma_f32 v241, v3, v132, v241
	v_add_f32_e32 v132, v240, v236
	v_add_f32_e32 v133, v241, v237
	s_add_i32 s60, s60, -1
	s_cmp_le_i32 s60, s26
	s_cbranch_scc1 .LBB0_509
	s_waitcnt vmcnt(0)
	v_mul_f32_e32 v240, v3, v133
	v_mul_f32_e32 v241, v2, v133
	v_fma_f32 v240, v2, v132, -v240
	v_fma_f32 v241, v3, v132, v241
	v_add_f32_e32 v132, v240, v238
	v_add_f32_e32 v133, v241, v239
	s_branch .LBB0_509

; __device__ __forceinline__ void ssm_p3(const Args& a, LAS unsigned char* lds, int layer, int G, int vb) {
;     ...
;         {
;             const int cb = (layer * 2 + 0) * 32 + g;
;             const f32x2 ab = AB[cb * 64 + lane], ap = AP[cb * 64 + lane];
;             const f32x2* se = SE + ((size_t)((b * 32 + g) * 2 + 0) * 8) * 64 + lane;
;             float sr = 0.f, si = 0.f;
;             for (int k = 0; k < seg && !DIAG_NOCARRY; ++k) { const f32x2 e = se[k * 64]; const float nr = ap[0] * sr - ap[1] * si + e[0], ni = ap[0] * si + ap[1] * sr + e[1]; sr = nr; si = ni; }
.LBB0_513:
	s_add_i32 s36, s27, s18
	v_lshl_or_b32 v2, s36, 6, v110
	v_ashrrev_i32_e32 v3, 31, v2
	v_lshl_add_u64 v[4:5], v[2:3], 3, s[8:9]
	global_load_dwordx2 v[126:127], v[4:5], off
	s_cmp_lt_i32 s26, 1
	s_cbranch_scc1 .LBB0_516
	v_lshl_add_u64 v[2:3], v[2:3], 3, s[76:77]
	global_load_dwordx2 v[2:3], v[2:3], off
	v_lshl_add_u64 v[4:5], v[120:121], 0, s[80:81]
	s_mov_b64 s[28:29], 0x200
	global_load_dwordx2 v[226:227], v[4:5], off
	v_lshl_add_u64 v[4:5], v[4:5], 0, s[28:29]
	global_load_dwordx2 v[228:229], v[4:5], off
	v_lshl_add_u64 v[4:5], v[4:5], 0, s[28:29]
	global_load_dwordx2 v[230:231], v[4:5], off
	v_lshl_add_u64 v[4:5], v[4:5], 0, s[28:29]
	global_load_dwordx2 v[232:233], v[4:5], off
	v_lshl_add_u64 v[4:5], v[4:5], 0, s[28:29]
	global_load_dwordx2 v[234:235], v[4:5], off
	v_lshl_add_u64 v[4:5], v[4:5], 0, s[28:29]
	global_load_dwordx2 v[236:237], v[4:5], off
	v_lshl_add_u64 v[4:5], v[4:5], 0, s[28:29]
	global_load_dwordx2 v[238:239], v[4:5], off
	v_mov_b32_e32 v156, 0
	v_mov_b32_e32 v157, 0
	s_waitcnt vmcnt(6)
	v_mul_f32_e32 v240, v3, v157
	v_mul_f32_e32 v241, v2, v157
	v_fma_f32 v240, v2, v156, -v240
	v_fma_f32 v241, v3, v156, v241
	v_add_f32_e32 v156, v240, v226
	v_add_f32_e32 v157, v241, v227
	s_add_i32 s26, s26, -1
	s_cmp_eq_u32 s26, 0
	s_cbranch_scc1 .LBB0_517
	s_waitcnt vmcnt(5)
	v_mul_f32_e32 v240, v3, v157
	v_mul_f32_e32 v241, v2, v157
	v_fma_f32 v240, v2, v156, -v240
	v_fma_f32 v241, v3, v156, v241
	v_add_f32_e32 v156, v240, v228
	v_add_f32_e32 v157, v241, v229
	s_add_i32 s26, s26, -1
	s_cmp_eq_u32 s26, 0
	s_cbranch_scc1 .LBB0_517
	s_waitcnt vmcnt(4)
	v_mul_f32_e32 v240, v3, v157
	v_mul_f32_e32 v241, v2, v157
	v_fma_f32 v240, v2, v156, -v240
	v_fma_f32 v241, v3, v156, v241
	v_add_f32_e32 v156, v240, v230
	v_add_f32_e32 v157, v241, v231
	s_add_i32 s26, s26, -1
	s_cmp_eq_u32 s26, 0
	s_cbranch_scc1 .LBB0_517
	s_waitcnt vmcnt(3)
	v_mul_f32_e32 v240, v3, v157
	v_mul_f32_e32 v241, v2, v157
	v_fma_f32 v240, v2, v156, -v240
	v_fma_f32 v241, v3, v156, v241
	v_add_f32_e32 v156, v240, v232
	v_add_f32_e32 v157, v241, v233
	s_add_i32 s26, s26, -1
	s_cmp_eq_u32 s26, 0
	s_cbranch_scc1 .LBB0_517
	s_waitcnt vmcnt(2)
	v_mul_f32_e32 v240, v3, v157
	v_mul_f32_e32 v241, v2, v157
	v_fma_f32 v240, v2, v156, -v240
	v_fma_f32 v241, v3, v156, v241
	v_add_f32_e32 v156, v240, v234
	v_add_f32_e32 v157, v241, v235
	s_add_i32 s26, s26, -1
	s_cmp_eq_u32 s26, 0
	s_cbranch_scc1 .LBB0_517
	s_waitcnt vmcnt(1)
	v_mul_f32_e32 v240, v3, v157
	v_mul_f32_e32 v241, v2, v157
	v_fma_f32 v240, v2, v156, -v240
	v_fma_f32 v241, v3, v156, v241
	v_add_f32_e32 v156, v240, v236
	v_add_f32_e32 v157, v241, v237
	s_add_i32 s26, s26, -1
	s_cmp_eq_u32 s26, 0
	s_cbranch_scc1 .LBB0_517
	s_waitcnt vmcnt(0)
	v_mul_f32_e32 v240, v3, v157
	v_mul_f32_e32 v241, v2, v157
	v_fma_f32 v240, v2, v156, -v240
	v_fma_f32 v241, v3, v156, v241
	v_add_f32_e32 v156, v240, v238
	v_add_f32_e32 v157, v241, v239
	s_branch .LBB0_517

; #define INP(k) inptr(k)
; #define WSPTR() kptr(224)
; #define OUTPTR() ((float*)kptr(216))
; __device__ __forceinline__ float bflo(unsigned w) { return __uint_as_float(w << 16); }
; __device__ __forceinline__ float bfhi(unsigned w) { return __uint_as_float(w & 0xffff0000u); }
; #define ssq ((float*)(WSPTR() + WS_SSQ))
; __device__ __forceinline__ void final_norm(const Args& a, int G, int vb) {
;     int tid_ = threadIdx.x; asm volatile("" : "+v"(tid_));
;     const int tid = tid_, lane = tid & 63, wave = __builtin_amdgcn_readfirstlane(tid >> 6);
;     const int gw = vb * NWAVES + wave, NGW = G * NWAVES;
;     const float* ssq = (const float*)(WSPTR() + WS_SSQ); const bf16* xb = (const bf16*)(WSPTR() + WS_XB); float* out = OUTPTR();
;     const f32x4* gn = (const f32x4*)INP(26) + 2 * lane;
;     f32x4 gv[2][2];
; #pragma unroll
;     for (int j = 0; j < 2; ++j) { gv[j][0] = gn[128 * j]; gv[j][1] = gn[128 * j + 1]; }
;     for (int mi = gw; mi < NT; mi += NGW) {
;         const int m = XCD_ROW(mi);
;         float s = (lane < 16) ? ssq[((size_t)(lane >> 2) * NT + m) * 4 + (lane & 3)] : 0.f; s = wave_sum(s);
;         const float rs = __builtin_amdgcn_rsqf(s * (1.0f / 1024.0f) + 1e-6f);
;         const u32x4* xr = (const u32x4*)(xb + (size_t)m * DM) + lane; f32x4* orow = (f32x4*)(out + (size_t)m * DM) + 2 * lane;
; #pragma unroll
;         for (int j = 0; j < 2; ++j) { const u32x4 w = xr[64 * j];
;             orow[128 * j] = (f32x4){bflo(w.x), bfhi(w.x), bflo(w.y), bfhi(w.y)} * rs * gv[j][0];
;             orow[128 * j + 1] = (f32x4){bflo(w.z), bfhi(w.z), bflo(w.w), bfhi(w.w)} * rs * gv[j][1]; }
;     }
.LBB0_826:
	v_readlane_b32 s3, v254, 0
	v_readfirstlane_b32 s5, v209
	s_ashr_i32 s4, s5, 6
	s_add_i32 s3, s4, s3
	s_movk_i32 s8, 0xe0
	s_movk_i32 s9, 0xe0
	s_movk_i32 s7, 0xd8
	s_movk_i32 s6, 0xd0
	s_cmpk_gt_i32 s3, 0x7fff
	s_cbranch_scc1 .LBB0_831
	s_ashr_i32 s11, s9, 31
	s_add_u32 s10, s0, s9
	s_addc_u32 s11, s1, s11
	s_ashr_i32 s9, s8, 31
	s_add_u32 s8, s0, s8
	s_addc_u32 s9, s1, s9
	s_ashr_i32 s13, s7, 31
	s_add_u32 s12, s0, s7
	s_addc_u32 s13, s1, s13
	s_ashr_i32 s7, s6, 31
	s_add_u32 s0, s0, s6
	s_addc_u32 s1, s1, s7
	s_load_dwordx2 s[0:1], s[0:1], 0x0
	v_and_b32_e32 v22, 63, v209
	v_lshlrev_b32_e32 v16, 5, v22
	s_waitcnt lgkmcnt(0)
	global_load_dwordx4 v[0:3], v16, s[0:1] offset:16
	global_load_dwordx4 v[4:7], v16, s[0:1]
	global_load_dwordx4 v[8:11], v16, s[0:1] offset:2064
	global_load_dwordx4 v[12:15], v16, s[0:1] offset:2048
	s_load_dwordx2 s[0:1], s[12:13], 0x0
	s_load_dwordx2 s[6:7], s[10:11], 0x0
	s_load_dwordx2 s[14:15], s[8:9], 0x0
	v_mov_b32_e32 v17, 0
	v_and_b32_e32 v20, 3, v209
	v_lshlrev_b32_e32 v20, 2, v20
	v_mov_b32_e32 v21, v17
	v_and_b32_e32 v23, 64, v218
	s_waitcnt lgkmcnt(0)
	v_lshl_add_u64 v[18:19], s[0:1], 0, v[16:17]
	v_lshl_add_u64 v[20:21], s[6:7], 0, v[20:21]
	s_mov_b64 s[0:1], 0x1d200000
	v_add_u32_e32 v23, 64, v23
	v_xor_b32_e32 v24, 1, v218
	v_lshl_add_u64 v[20:21], v[20:21], 0, s[0:1]
	v_cmp_lt_i32_e64 s[0:1], v24, v23
	v_xor_b32_e32 v25, 2, v218
	v_xor_b32_e32 v26, 4, v218
	v_cndmask_b32_e64 v24, v218, v24, s[0:1]
	v_cmp_lt_i32_e64 s[0:1], v25, v23
	v_xor_b32_e32 v27, 8, v218
	v_xor_b32_e32 v28, 16, v218
	v_cndmask_b32_e64 v25, v218, v25, s[0:1]
	v_cmp_lt_i32_e64 s[0:1], v26, v23
	v_xor_b32_e32 v29, 32, v218
	v_cmp_gt_u32_e32 vcc, 16, v22
	v_cndmask_b32_e64 v26, v218, v26, s[0:1]
	v_cmp_lt_i32_e64 s[0:1], v27, v23
	v_lshlrev_b32_e32 v22, 4, v22
	v_lshlrev_b32_e32 v16, 13, v209
	v_cndmask_b32_e64 v27, v218, v27, s[0:1]
	v_cmp_lt_i32_e64 s[0:1], v28, v23
	v_and_b32_e32 v16, 0x18000, v16
	v_lshlrev_b32_e32 v24, 2, v24
	v_cndmask_b32_e64 v28, v218, v28, s[0:1]
	v_cmp_lt_i32_e64 s[0:1], v29, v23
	v_lshlrev_b32_e32 v25, 2, v25
	v_lshlrev_b32_e32 v26, 2, v26
	v_cndmask_b32_e64 v23, v218, v29, s[0:1]
	v_lshlrev_b32_e32 v29, 2, v23
	v_mov_b32_e32 v23, v17
	v_lshl_add_u64 v[22:23], s[14:15], 0, v[22:23]
	s_mov_b64 s[0:1], 0x9800000
	v_lshl_add_u64 v[22:23], v[22:23], 0, s[0:1]
	s_lshl_b32 s0, s33, 12
	s_lshl_b32 s1, s4, 9
	v_lshlrev_b32_e32 v27, 2, v27
	v_lshlrev_b32_e32 v28, 2, v28
	s_bfe_u32 s6, s5, 0x30006
	s_add_i32 s7, s0, s1
	s_lshl_b32 s8, s20, 12
	v_mov_b32_e32 v30, 0x358637bd
	s_cmpk_lg_i32 s2, 0x800
	s_cbranch_scc1 .LBB0_829
	s_ashr_i32 s1, s3, 3
	s_and_b32 s0, s7, 0x7000
	s_and_b32 s1, s1, -8
	s_add_i32 s0, s0, s1
	s_or_b32 s0, s0, s6
	s_ashr_i32 s1, s0, 31
	s_add_i32 s3, s3, s2
	s_add_i32 s7, s7, s8
	v_mov_b32_e32 v31, 0
	s_and_saveexec_b64 s[4:5], vcc
	v_lshl_add_u64 v[54:55], s[0:1], 0, v[16:17]
	v_lshl_add_u64 v[54:55], v[54:55], 4, v[20:21]
	global_load_dword v31, v[54:55], off
	s_or_b64 exec, exec, s[4:5]
	s_lshl_b64 s[4:5], s[0:1], 11
	v_lshl_add_u64 v[54:55], v[22:23], 0, s[4:5]
	global_load_dwordx4 v[32:35], v[54:55], off
	global_load_dwordx4 v[36:39], v[54:55], off offset:1024
	s_lshl_b64 s[4:5], s[0:1], 12
	v_lshl_add_u64 v[40:41], v[18:19], 0, s[4:5]
	s_ashr_i32 s1, s3, 3
	s_and_b32 s0, s7, 0x7000
	s_and_b32 s1, s1, -8
	s_add_i32 s0, s0, s1
	s_or_b32 s0, s0, s6
	s_ashr_i32 s1, s0, 31
	s_add_i32 s3, s3, s2
	s_add_i32 s7, s7, s8
	v_mov_b32_e32 v42, 0
	s_and_saveexec_b64 s[4:5], vcc
	v_lshl_add_u64 v[54:55], s[0:1], 0, v[16:17]
	v_lshl_add_u64 v[54:55], v[54:55], 4, v[20:21]
	global_load_dword v42, v[54:55], off
	s_or_b64 exec, exec, s[4:5]
	s_lshl_b64 s[4:5], s[0:1], 11
	v_lshl_add_u64 v[54:55], v[22:23], 0, s[4:5]
	global_load_dwordx4 v[44:47], v[54:55], off
	global_load_dwordx4 v[48:51], v[54:55], off offset:1024
	s_lshl_b64 s[4:5], s[0:1], 12
	v_lshl_add_u64 v[52:53], v[18:19], 0, s[4:5]
	s_waitcnt vmcnt(3)
	ds_bpermute_b32 v56, v24, v31
	s_waitcnt lgkmcnt(0)
	v_add_f32_e32 v31, v31, v56
	ds_bpermute_b32 v56, v25, v31
	s_waitcnt lgkmcnt(0)
	v_add_f32_e32 v31, v31, v56
	ds_bpermute_b32 v56, v26, v31
	s_waitcnt lgkmcnt(0)
	v_add_f32_e32 v31, v31, v56
	ds_bpermute_b32 v56, v27, v31
	s_waitcnt lgkmcnt(0)
	v_add_f32_e32 v31, v31, v56
	ds_bpermute_b32 v56, v28, v31
	s_waitcnt lgkmcnt(0)
	v_add_f32_e32 v31, v31, v56
	ds_bpermute_b32 v56, v29, v31
	s_waitcnt lgkmcnt(0)
	v_add_f32_e32 v31, v31, v56
	v_fmamk_f32 v31, v31, 0x3a800000, v30
	v_rsq_f32_e32 v80, v31
	v_mov_b32_e32 v81, v17
	v_lshlrev_b32_e32 v56, 16, v32
	v_and_b32_e32 v57, 0xffff0000, v32
	v_lshlrev_b32_e32 v58, 16, v33
	v_and_b32_e32 v59, 0xffff0000, v33
	v_lshlrev_b32_e32 v60, 16, v34
	v_and_b32_e32 v61, 0xffff0000, v34
	v_lshlrev_b32_e32 v62, 16, v35
	v_and_b32_e32 v63, 0xffff0000, v35
	v_pk_mul_f32 v[56:57], v[80:81], v[56:57] op_sel_hi:[0,1]
	v_pk_mul_f32 v[58:59], v[80:81], v[58:59] op_sel_hi:[0,1]
	v_pk_mul_f32 v[60:61], v[80:81], v[60:61] op_sel_hi:[0,1]
	v_pk_mul_f32 v[62:63], v[80:81], v[62:63] op_sel_hi:[0,1]
	v_pk_mul_f32 v[64:65], v[4:5], v[56:57]
	v_pk_mul_f32 v[66:67], v[6:7], v[58:59]
	v_pk_mul_f32 v[68:69], v[0:1], v[60:61]
	v_pk_mul_f32 v[70:71], v[2:3], v[62:63]
	v_lshlrev_b32_e32 v56, 16, v36
	v_and_b32_e32 v57, 0xffff0000, v36
	v_lshlrev_b32_e32 v58, 16, v37
	v_and_b32_e32 v59, 0xffff0000, v37
	v_lshlrev_b32_e32 v60, 16, v38
	v_and_b32_e32 v61, 0xffff0000, v38
	v_lshlrev_b32_e32 v62, 16, v39
	v_and_b32_e32 v63, 0xffff0000, v39
	v_pk_mul_f32 v[56:57], v[80:81], v[56:57] op_sel_hi:[0,1]
	v_pk_mul_f32 v[58:59], v[80:81], v[58:59] op_sel_hi:[0,1]
	v_pk_mul_f32 v[60:61], v[80:81], v[60:61] op_sel_hi:[0,1]
	v_pk_mul_f32 v[62:63], v[80:81], v[62:63] op_sel_hi:[0,1]
	v_pk_mul_f32 v[72:73], v[12:13], v[56:57]
	v_pk_mul_f32 v[74:75], v[14:15], v[58:59]
	v_pk_mul_f32 v[76:77], v[8:9], v[60:61]
	v_pk_mul_f32 v[78:79], v[10:11], v[62:63]
	v_mov_b64_e32 v[82:83], v[40:41]
	s_ashr_i32 s1, s3, 3
	s_and_b32 s0, s7, 0x7000
	s_and_b32 s1, s1, -8
	s_add_i32 s0, s0, s1
	s_or_b32 s0, s0, s6
	s_ashr_i32 s1, s0, 31
	s_add_i32 s3, s3, s2
	s_add_i32 s7, s7, s8
	v_mov_b32_e32 v31, 0
	s_and_saveexec_b64 s[4:5], vcc
	v_lshl_add_u64 v[54:55], s[0:1], 0, v[16:17]
	v_lshl_add_u64 v[54:55], v[54:55], 4, v[20:21]
	global_load_dword v31, v[54:55], off
	s_or_b64 exec, exec, s[4:5]
	s_lshl_b64 s[4:5], s[0:1], 11
	v_lshl_add_u64 v[54:55], v[22:23], 0, s[4:5]
	global_load_dwordx4 v[32:35], v[54:55], off
	global_load_dwordx4 v[36:39], v[54:55], off offset:1024
	s_lshl_b64 s[4:5], s[0:1], 12
	v_lshl_add_u64 v[40:41], v[18:19], 0, s[4:5]
	global_store_dwordx4 v[82:83], v[64:67], off
	global_store_dwordx4 v[82:83], v[68:71], off offset:16
	global_store_dwordx4 v[82:83], v[72:75], off offset:2048
	global_store_dwordx4 v[82:83], v[76:79], off offset:2064
	s_waitcnt vmcnt(7)
; __device__ __forceinline__ float bflo(unsigned w) { return __uint_as_float(w << 16); }
; __device__ __forceinline__ float bfhi(unsigned w) { return __uint_as_float(w & 0xffff0000u); }
; #define ssq ((float*)(WSPTR() + WS_SSQ))
; __device__ __forceinline__ void final_norm(const Args& a, int G, int vb) {
;     ...
;     for (int mi = gw; mi < NT; mi += NGW) {
;         const int m = XCD_ROW(mi);
;         float s = (lane < 16) ? ssq[((size_t)(lane >> 2) * NT + m) * 4 + (lane & 3)] : 0.f; s = wave_sum(s);
;         const float rs = __builtin_amdgcn_rsqf(s * (1.0f / 1024.0f) + 1e-6f);
;         const u32x4* xr = (const u32x4*)(xb + (size_t)m * DM) + lane; f32x4* orow = (f32x4*)(out + (size_t)m * DM) + 2 * lane;
; #pragma unroll
;         for (int j = 0; j < 2; ++j) { const u32x4 w = xr[64 * j];
;             orow[128 * j] = (f32x4){bflo(w.x), bfhi(w.x), bflo(w.y), bfhi(w.y)} * rs * gv[j][0];
;             orow[128 * j + 1] = (f32x4){bflo(w.z), bfhi(w.z), bflo(w.w), bfhi(w.w)} * rs * gv[j][1]; }
;     }
	ds_bpermute_b32 v56, v24, v42
	s_waitcnt lgkmcnt(0)
	v_add_f32_e32 v42, v42, v56
	ds_bpermute_b32 v56, v25, v42
	s_waitcnt lgkmcnt(0)
	v_add_f32_e32 v42, v42, v56
	ds_bpermute_b32 v56, v26, v42
	s_waitcnt lgkmcnt(0)
	v_add_f32_e32 v42, v42, v56
	ds_bpermute_b32 v56, v27, v42
	s_waitcnt lgkmcnt(0)
	v_add_f32_e32 v42, v42, v56
	ds_bpermute_b32 v56, v28, v42
	s_waitcnt lgkmcnt(0)
	v_add_f32_e32 v42, v42, v56
	ds_bpermute_b32 v56, v29, v42
	s_waitcnt lgkmcnt(0)
	v_add_f32_e32 v42, v42, v56
	v_fmamk_f32 v42, v42, 0x3a800000, v30
	v_rsq_f32_e32 v80, v42
	v_mov_b32_e32 v81, v17
	v_lshlrev_b32_e32 v56, 16, v44
	v_and_b32_e32 v57, 0xffff0000, v44
	v_lshlrev_b32_e32 v58, 16, v45
	v_and_b32_e32 v59, 0xffff0000, v45
	v_lshlrev_b32_e32 v60, 16, v46
	v_and_b32_e32 v61, 0xffff0000, v46
	v_lshlrev_b32_e32 v62, 16, v47
	v_and_b32_e32 v63, 0xffff0000, v47
	v_pk_mul_f32 v[56:57], v[80:81], v[56:57] op_sel_hi:[0,1]
	v_pk_mul_f32 v[58:59], v[80:81], v[58:59] op_sel_hi:[0,1]
	v_pk_mul_f32 v[60:61], v[80:81], v[60:61] op_sel_hi:[0,1]
	v_pk_mul_f32 v[62:63], v[80:81], v[62:63] op_sel_hi:[0,1]
	v_pk_mul_f32 v[64:65], v[4:5], v[56:57]
	v_pk_mul_f32 v[66:67], v[6:7], v[58:59]
	v_pk_mul_f32 v[68:69], v[0:1], v[60:61]
	v_pk_mul_f32 v[70:71], v[2:3], v[62:63]
	v_lshlrev_b32_e32 v56, 16, v48
	v_and_b32_e32 v57, 0xffff0000, v48
	v_lshlrev_b32_e32 v58, 16, v49
	v_and_b32_e32 v59, 0xffff0000, v49
	v_lshlrev_b32_e32 v60, 16, v50
	v_and_b32_e32 v61, 0xffff0000, v50
	v_lshlrev_b32_e32 v62, 16, v51
	v_and_b32_e32 v63, 0xffff0000, v51
	v_pk_mul_f32 v[56:57], v[80:81], v[56:57] op_sel_hi:[0,1]
	v_pk_mul_f32 v[58:59], v[80:81], v[58:59] op_sel_hi:[0,1]
	v_pk_mul_f32 v[60:61], v[80:81], v[60:61] op_sel_hi:[0,1]
	v_pk_mul_f32 v[62:63], v[80:81], v[62:63] op_sel_hi:[0,1]
	v_pk_mul_f32 v[72:73], v[12:13], v[56:57]
	v_pk_mul_f32 v[74:75], v[14:15], v[58:59]
	v_pk_mul_f32 v[76:77], v[8:9], v[60:61]
	v_pk_mul_f32 v[78:79], v[10:11], v[62:63]
	v_mov_b64_e32 v[82:83], v[52:53]
	s_ashr_i32 s1, s3, 3
	s_and_b32 s0, s7, 0x7000
	s_and_b32 s1, s1, -8
	s_add_i32 s0, s0, s1
	s_or_b32 s0, s0, s6
	s_ashr_i32 s1, s0, 31
	s_add_i32 s3, s3, s2
	s_add_i32 s7, s7, s8
	v_mov_b32_e32 v42, 0
	s_and_saveexec_b64 s[4:5], vcc
	v_lshl_add_u64 v[54:55], s[0:1], 0, v[16:17]
	v_lshl_add_u64 v[54:55], v[54:55], 4, v[20:21]
	global_load_dword v42, v[54:55], off
	s_or_b64 exec, exec, s[4:5]
	s_lshl_b64 s[4:5], s[0:1], 11
	v_lshl_add_u64 v[54:55], v[22:23], 0, s[4:5]
	global_load_dwordx4 v[44:47], v[54:55], off
	global_load_dwordx4 v[48:51], v[54:55], off offset:1024
	s_lshl_b64 s[4:5], s[0:1], 12
	v_lshl_add_u64 v[52:53], v[18:19], 0, s[4:5]
	global_store_dwordx4 v[82:83], v[64:67], off
	global_store_dwordx4 v[82:83], v[68:71], off offset:16
	global_store_dwordx4 v[82:83], v[72:75], off offset:2048
	global_store_dwordx4 v[82:83], v[76:79], off offset:2064
	s_waitcnt vmcnt(11)
	ds_bpermute_b32 v56, v24, v31
	s_waitcnt lgkmcnt(0)
	v_add_f32_e32 v31, v31, v56
	ds_bpermute_b32 v56, v25, v31
	s_waitcnt lgkmcnt(0)
	v_add_f32_e32 v31, v31, v56
	ds_bpermute_b32 v56, v26, v31
	s_waitcnt lgkmcnt(0)
	v_add_f32_e32 v31, v31, v56
	ds_bpermute_b32 v56, v27, v31
	s_waitcnt lgkmcnt(0)
	v_add_f32_e32 v31, v31, v56
	ds_bpermute_b32 v56, v28, v31
	s_waitcnt lgkmcnt(0)
	v_add_f32_e32 v31, v31, v56
	ds_bpermute_b32 v56, v29, v31
	s_waitcnt lgkmcnt(0)
	v_add_f32_e32 v31, v31, v56
	v_fmamk_f32 v31, v31, 0x3a800000, v30
	v_rsq_f32_e32 v80, v31
	v_mov_b32_e32 v81, v17
	v_lshlrev_b32_e32 v56, 16, v32
	v_and_b32_e32 v57, 0xffff0000, v32
	v_lshlrev_b32_e32 v58, 16, v33
	v_and_b32_e32 v59, 0xffff0000, v33
	v_lshlrev_b32_e32 v60, 16, v34
	v_and_b32_e32 v61, 0xffff0000, v34
	v_lshlrev_b32_e32 v62, 16, v35
	v_and_b32_e32 v63, 0xffff0000, v35
	v_pk_mul_f32 v[56:57], v[80:81], v[56:57] op_sel_hi:[0,1]
	v_pk_mul_f32 v[58:59], v[80:81], v[58:59] op_sel_hi:[0,1]
	v_pk_mul_f32 v[60:61], v[80:81], v[60:61] op_sel_hi:[0,1]
	v_pk_mul_f32 v[62:63], v[80:81], v[62:63] op_sel_hi:[0,1]
	v_pk_mul_f32 v[64:65], v[4:5], v[56:57]
	v_pk_mul_f32 v[66:67], v[6:7], v[58:59]
	v_pk_mul_f32 v[68:69], v[0:1], v[60:61]
	v_pk_mul_f32 v[70:71], v[2:3], v[62:63]
	v_lshlrev_b32_e32 v56, 16, v36
	v_and_b32_e32 v57, 0xffff0000, v36
	v_lshlrev_b32_e32 v58, 16, v37
	v_and_b32_e32 v59, 0xffff0000, v37
	v_lshlrev_b32_e32 v60, 16, v38
	v_and_b32_e32 v61, 0xffff0000, v38
	v_lshlrev_b32_e32 v62, 16, v39
	v_and_b32_e32 v63, 0xffff0000, v39
	v_pk_mul_f32 v[56:57], v[80:81], v[56:57] op_sel_hi:[0,1]
	v_pk_mul_f32 v[58:59], v[80:81], v[58:59] op_sel_hi:[0,1]
	v_pk_mul_f32 v[60:61], v[80:81], v[60:61] op_sel_hi:[0,1]
	v_pk_mul_f32 v[62:63], v[80:81], v[62:63] op_sel_hi:[0,1]
	v_pk_mul_f32 v[72:73], v[12:13], v[56:57]
	v_pk_mul_f32 v[74:75], v[14:15], v[58:59]
	v_pk_mul_f32 v[76:77], v[8:9], v[60:61]
	v_pk_mul_f32 v[78:79], v[10:11], v[62:63]
	v_mov_b64_e32 v[82:83], v[40:41]
	s_ashr_i32 s1, s3, 3
	s_and_b32 s0, s7, 0x7000
	s_and_b32 s1, s1, -8
	s_add_i32 s0, s0, s1
	s_or_b32 s0, s0, s6
	s_ashr_i32 s1, s0, 31
	s_add_i32 s3, s3, s2
	s_add_i32 s7, s7, s8
	v_mov_b32_e32 v31, 0
	s_and_saveexec_b64 s[4:5], vcc
	v_lshl_add_u64 v[54:55], s[0:1], 0, v[16:17]
	v_lshl_add_u64 v[54:55], v[54:55], 4, v[20:21]
	global_load_dword v31, v[54:55], off
	s_or_b64 exec, exec, s[4:5]
	s_lshl_b64 s[4:5], s[0:1], 11
	v_lshl_add_u64 v[54:55], v[22:23], 0, s[4:5]
	global_load_dwordx4 v[32:35], v[54:55], off
	global_load_dwordx4 v[36:39], v[54:55], off offset:1024
	s_lshl_b64 s[4:5], s[0:1], 12
	v_lshl_add_u64 v[40:41], v[18:19], 0, s[4:5]
	global_store_dwordx4 v[82:83], v[64:67], off
	global_store_dwordx4 v[82:83], v[68:71], off offset:16
	global_store_dwordx4 v[82:83], v[72:75], off offset:2048
	global_store_dwordx4 v[82:83], v[76:79], off offset:2064
	s_waitcnt vmcnt(11)
; __device__ __forceinline__ float bflo(unsigned w) { return __uint_as_float(w << 16); }
; __device__ __forceinline__ float bfhi(unsigned w) { return __uint_as_float(w & 0xffff0000u); }
; #define ssq ((float*)(WSPTR() + WS_SSQ))
; __device__ __forceinline__ void final_norm(const Args& a, int G, int vb) {
;     ...
;     for (int mi = gw; mi < NT; mi += NGW) {
;         const int m = XCD_ROW(mi);
;         float s = (lane < 16) ? ssq[((size_t)(lane >> 2) * NT + m) * 4 + (lane & 3)] : 0.f; s = wave_sum(s);
;         const float rs = __builtin_amdgcn_rsqf(s * (1.0f / 1024.0f) + 1e-6f);
;         const u32x4* xr = (const u32x4*)(xb + (size_t)m * DM) + lane; f32x4* orow = (f32x4*)(out + (size_t)m * DM) + 2 * lane;
; #pragma unroll
;         for (int j = 0; j < 2; ++j) { const u32x4 w = xr[64 * j];
;             orow[128 * j] = (f32x4){bflo(w.x), bfhi(w.x), bflo(w.y), bfhi(w.y)} * rs * gv[j][0];
;             orow[128 * j + 1] = (f32x4){bflo(w.z), bfhi(w.z), bflo(w.w), bfhi(w.w)} * rs * gv[j][1]; }
;     }
	ds_bpermute_b32 v56, v24, v42
	s_waitcnt lgkmcnt(0)
	v_add_f32_e32 v42, v42, v56
	ds_bpermute_b32 v56, v25, v42
	s_waitcnt lgkmcnt(0)
	v_add_f32_e32 v42, v42, v56
	ds_bpermute_b32 v56, v26, v42
	s_waitcnt lgkmcnt(0)
	v_add_f32_e32 v42, v42, v56
	ds_bpermute_b32 v56, v27, v42
	s_waitcnt lgkmcnt(0)
	v_add_f32_e32 v42, v42, v56
	ds_bpermute_b32 v56, v28, v42
	s_waitcnt lgkmcnt(0)
	v_add_f32_e32 v42, v42, v56
	ds_bpermute_b32 v56, v29, v42
	s_waitcnt lgkmcnt(0)
	v_add_f32_e32 v42, v42, v56
	v_fmamk_f32 v42, v42, 0x3a800000, v30
	v_rsq_f32_e32 v80, v42
	v_mov_b32_e32 v81, v17
	v_lshlrev_b32_e32 v56, 16, v44
	v_and_b32_e32 v57, 0xffff0000, v44
	v_lshlrev_b32_e32 v58, 16, v45
	v_and_b32_e32 v59, 0xffff0000, v45
	v_lshlrev_b32_e32 v60, 16, v46
	v_and_b32_e32 v61, 0xffff0000, v46
	v_lshlrev_b32_e32 v62, 16, v47
	v_and_b32_e32 v63, 0xffff0000, v47
	v_pk_mul_f32 v[56:57], v[80:81], v[56:57] op_sel_hi:[0,1]
	v_pk_mul_f32 v[58:59], v[80:81], v[58:59] op_sel_hi:[0,1]
	v_pk_mul_f32 v[60:61], v[80:81], v[60:61] op_sel_hi:[0,1]
	v_pk_mul_f32 v[62:63], v[80:81], v[62:63] op_sel_hi:[0,1]
	v_pk_mul_f32 v[64:65], v[4:5], v[56:57]
	v_pk_mul_f32 v[66:67], v[6:7], v[58:59]
	v_pk_mul_f32 v[68:69], v[0:1], v[60:61]
	v_pk_mul_f32 v[70:71], v[2:3], v[62:63]
	v_lshlrev_b32_e32 v56, 16, v48
	v_and_b32_e32 v57, 0xffff0000, v48
	v_lshlrev_b32_e32 v58, 16, v49
	v_and_b32_e32 v59, 0xffff0000, v49
	v_lshlrev_b32_e32 v60, 16, v50
	v_and_b32_e32 v61, 0xffff0000, v50
	v_lshlrev_b32_e32 v62, 16, v51
	v_and_b32_e32 v63, 0xffff0000, v51
	v_pk_mul_f32 v[56:57], v[80:81], v[56:57] op_sel_hi:[0,1]
	v_pk_mul_f32 v[58:59], v[80:81], v[58:59] op_sel_hi:[0,1]
	v_pk_mul_f32 v[60:61], v[80:81], v[60:61] op_sel_hi:[0,1]
	v_pk_mul_f32 v[62:63], v[80:81], v[62:63] op_sel_hi:[0,1]
	v_pk_mul_f32 v[72:73], v[12:13], v[56:57]
	v_pk_mul_f32 v[74:75], v[14:15], v[58:59]
	v_pk_mul_f32 v[76:77], v[8:9], v[60:61]
	v_pk_mul_f32 v[78:79], v[10:11], v[62:63]
	v_mov_b64_e32 v[82:83], v[52:53]
	s_ashr_i32 s1, s3, 3
	s_and_b32 s0, s7, 0x7000
	s_and_b32 s1, s1, -8
	s_add_i32 s0, s0, s1
	s_or_b32 s0, s0, s6
	s_ashr_i32 s1, s0, 31
	s_add_i32 s3, s3, s2
	s_add_i32 s7, s7, s8
	v_mov_b32_e32 v42, 0
	s_and_saveexec_b64 s[4:5], vcc
	v_lshl_add_u64 v[54:55], s[0:1], 0, v[16:17]
	v_lshl_add_u64 v[54:55], v[54:55], 4, v[20:21]
	global_load_dword v42, v[54:55], off
	s_or_b64 exec, exec, s[4:5]
	s_lshl_b64 s[4:5], s[0:1], 11
	v_lshl_add_u64 v[54:55], v[22:23], 0, s[4:5]
	global_load_dwordx4 v[44:47], v[54:55], off
	global_load_dwordx4 v[48:51], v[54:55], off offset:1024
	s_lshl_b64 s[4:5], s[0:1], 12
	v_lshl_add_u64 v[52:53], v[18:19], 0, s[4:5]
	global_store_dwordx4 v[82:83], v[64:67], off
	global_store_dwordx4 v[82:83], v[68:71], off offset:16
	global_store_dwordx4 v[82:83], v[72:75], off offset:2048
	global_store_dwordx4 v[82:83], v[76:79], off offset:2064
	s_waitcnt vmcnt(11)
	ds_bpermute_b32 v56, v24, v31
	s_waitcnt lgkmcnt(0)
	v_add_f32_e32 v31, v31, v56
	ds_bpermute_b32 v56, v25, v31
	s_waitcnt lgkmcnt(0)
	v_add_f32_e32 v31, v31, v56
	ds_bpermute_b32 v56, v26, v31
	s_waitcnt lgkmcnt(0)
	v_add_f32_e32 v31, v31, v56
	ds_bpermute_b32 v56, v27, v31
	s_waitcnt lgkmcnt(0)
	v_add_f32_e32 v31, v31, v56
	ds_bpermute_b32 v56, v28, v31
	s_waitcnt lgkmcnt(0)
	v_add_f32_e32 v31, v31, v56
	ds_bpermute_b32 v56, v29, v31
	s_waitcnt lgkmcnt(0)
	v_add_f32_e32 v31, v31, v56
	v_fmamk_f32 v31, v31, 0x3a800000, v30
	v_rsq_f32_e32 v80, v31
	v_mov_b32_e32 v81, v17
	v_lshlrev_b32_e32 v56, 16, v32
	v_and_b32_e32 v57, 0xffff0000, v32
	v_lshlrev_b32_e32 v58, 16, v33
	v_and_b32_e32 v59, 0xffff0000, v33
	v_lshlrev_b32_e32 v60, 16, v34
	v_and_b32_e32 v61, 0xffff0000, v34
	v_lshlrev_b32_e32 v62, 16, v35
	v_and_b32_e32 v63, 0xffff0000, v35
	v_pk_mul_f32 v[56:57], v[80:81], v[56:57] op_sel_hi:[0,1]
	v_pk_mul_f32 v[58:59], v[80:81], v[58:59] op_sel_hi:[0,1]
	v_pk_mul_f32 v[60:61], v[80:81], v[60:61] op_sel_hi:[0,1]
	v_pk_mul_f32 v[62:63], v[80:81], v[62:63] op_sel_hi:[0,1]
	v_pk_mul_f32 v[64:65], v[4:5], v[56:57]
	v_pk_mul_f32 v[66:67], v[6:7], v[58:59]
	v_pk_mul_f32 v[68:69], v[0:1], v[60:61]
	v_pk_mul_f32 v[70:71], v[2:3], v[62:63]
	v_lshlrev_b32_e32 v56, 16, v36
	v_and_b32_e32 v57, 0xffff0000, v36
	v_lshlrev_b32_e32 v58, 16, v37
	v_and_b32_e32 v59, 0xffff0000, v37
	v_lshlrev_b32_e32 v60, 16, v38
	v_and_b32_e32 v61, 0xffff0000, v38
	v_lshlrev_b32_e32 v62, 16, v39
	v_and_b32_e32 v63, 0xffff0000, v39
	v_pk_mul_f32 v[56:57], v[80:81], v[56:57] op_sel_hi:[0,1]
	v_pk_mul_f32 v[58:59], v[80:81], v[58:59] op_sel_hi:[0,1]
	v_pk_mul_f32 v[60:61], v[80:81], v[60:61] op_sel_hi:[0,1]
	v_pk_mul_f32 v[62:63], v[80:81], v[62:63] op_sel_hi:[0,1]
	v_pk_mul_f32 v[72:73], v[12:13], v[56:57]
	v_pk_mul_f32 v[74:75], v[14:15], v[58:59]
	v_pk_mul_f32 v[76:77], v[8:9], v[60:61]
	v_pk_mul_f32 v[78:79], v[10:11], v[62:63]
	v_mov_b64_e32 v[82:83], v[40:41]
	s_ashr_i32 s1, s3, 3
	s_and_b32 s0, s7, 0x7000
	s_and_b32 s1, s1, -8
	s_add_i32 s0, s0, s1
	s_or_b32 s0, s0, s6
	s_ashr_i32 s1, s0, 31
	s_add_i32 s3, s3, s2
	s_add_i32 s7, s7, s8
	v_mov_b32_e32 v31, 0
	s_and_saveexec_b64 s[4:5], vcc
	v_lshl_add_u64 v[54:55], s[0:1], 0, v[16:17]
	v_lshl_add_u64 v[54:55], v[54:55], 4, v[20:21]
	global_load_dword v31, v[54:55], off
	s_or_b64 exec, exec, s[4:5]
	s_lshl_b64 s[4:5], s[0:1], 11
	v_lshl_add_u64 v[54:55], v[22:23], 0, s[4:5]
	global_load_dwordx4 v[32:35], v[54:55], off
	global_load_dwordx4 v[36:39], v[54:55], off offset:1024
	s_lshl_b64 s[4:5], s[0:1], 12
	v_lshl_add_u64 v[40:41], v[18:19], 0, s[4:5]
	global_store_dwordx4 v[82:83], v[64:67], off
	global_store_dwordx4 v[82:83], v[68:71], off offset:16
	global_store_dwordx4 v[82:83], v[72:75], off offset:2048
	global_store_dwordx4 v[82:83], v[76:79], off offset:2064
	s_waitcnt vmcnt(11)
; __device__ __forceinline__ float bflo(unsigned w) { return __uint_as_float(w << 16); }
; __device__ __forceinline__ float bfhi(unsigned w) { return __uint_as_float(w & 0xffff0000u); }
; #define ssq ((float*)(WSPTR() + WS_SSQ))
; __device__ __forceinline__ void final_norm(const Args& a, int G, int vb) {
;     ...
;     for (int mi = gw; mi < NT; mi += NGW) {
;         const int m = XCD_ROW(mi);
;         float s = (lane < 16) ? ssq[((size_t)(lane >> 2) * NT + m) * 4 + (lane & 3)] : 0.f; s = wave_sum(s);
;         const float rs = __builtin_amdgcn_rsqf(s * (1.0f / 1024.0f) + 1e-6f);
;         const u32x4* xr = (const u32x4*)(xb + (size_t)m * DM) + lane; f32x4* orow = (f32x4*)(out + (size_t)m * DM) + 2 * lane;
; #pragma unroll
;         for (int j = 0; j < 2; ++j) { const u32x4 w = xr[64 * j];
;             orow[128 * j] = (f32x4){bflo(w.x), bfhi(w.x), bflo(w.y), bfhi(w.y)} * rs * gv[j][0];
;             orow[128 * j + 1] = (f32x4){bflo(w.z), bfhi(w.z), bflo(w.w), bfhi(w.w)} * rs * gv[j][1]; }
;     }
	ds_bpermute_b32 v56, v24, v42
	s_waitcnt lgkmcnt(0)
	v_add_f32_e32 v42, v42, v56
	ds_bpermute_b32 v56, v25, v42
	s_waitcnt lgkmcnt(0)
	v_add_f32_e32 v42, v42, v56
	ds_bpermute_b32 v56, v26, v42
	s_waitcnt lgkmcnt(0)
	v_add_f32_e32 v42, v42, v56
	ds_bpermute_b32 v56, v27, v42
	s_waitcnt lgkmcnt(0)
	v_add_f32_e32 v42, v42, v56
	ds_bpermute_b32 v56, v28, v42
	s_waitcnt lgkmcnt(0)
	v_add_f32_e32 v42, v42, v56
	ds_bpermute_b32 v56, v29, v42
	s_waitcnt lgkmcnt(0)
	v_add_f32_e32 v42, v42, v56
	v_fmamk_f32 v42, v42, 0x3a800000, v30
	v_rsq_f32_e32 v80, v42
	v_mov_b32_e32 v81, v17
	v_lshlrev_b32_e32 v56, 16, v44
	v_and_b32_e32 v57, 0xffff0000, v44
	v_lshlrev_b32_e32 v58, 16, v45
	v_and_b32_e32 v59, 0xffff0000, v45
	v_lshlrev_b32_e32 v60, 16, v46
	v_and_b32_e32 v61, 0xffff0000, v46
	v_lshlrev_b32_e32 v62, 16, v47
	v_and_b32_e32 v63, 0xffff0000, v47
	v_pk_mul_f32 v[56:57], v[80:81], v[56:57] op_sel_hi:[0,1]
	v_pk_mul_f32 v[58:59], v[80:81], v[58:59] op_sel_hi:[0,1]
	v_pk_mul_f32 v[60:61], v[80:81], v[60:61] op_sel_hi:[0,1]
	v_pk_mul_f32 v[62:63], v[80:81], v[62:63] op_sel_hi:[0,1]
	v_pk_mul_f32 v[64:65], v[4:5], v[56:57]
	v_pk_mul_f32 v[66:67], v[6:7], v[58:59]
	v_pk_mul_f32 v[68:69], v[0:1], v[60:61]
	v_pk_mul_f32 v[70:71], v[2:3], v[62:63]
	v_lshlrev_b32_e32 v56, 16, v48
	v_and_b32_e32 v57, 0xffff0000, v48
	v_lshlrev_b32_e32 v58, 16, v49
	v_and_b32_e32 v59, 0xffff0000, v49
	v_lshlrev_b32_e32 v60, 16, v50
	v_and_b32_e32 v61, 0xffff0000, v50
	v_lshlrev_b32_e32 v62, 16, v51
	v_and_b32_e32 v63, 0xffff0000, v51
	v_pk_mul_f32 v[56:57], v[80:81], v[56:57] op_sel_hi:[0,1]
	v_pk_mul_f32 v[58:59], v[80:81], v[58:59] op_sel_hi:[0,1]
	v_pk_mul_f32 v[60:61], v[80:81], v[60:61] op_sel_hi:[0,1]
	v_pk_mul_f32 v[62:63], v[80:81], v[62:63] op_sel_hi:[0,1]
	v_pk_mul_f32 v[72:73], v[12:13], v[56:57]
	v_pk_mul_f32 v[74:75], v[14:15], v[58:59]
	v_pk_mul_f32 v[76:77], v[8:9], v[60:61]
	v_pk_mul_f32 v[78:79], v[10:11], v[62:63]
	v_mov_b64_e32 v[82:83], v[52:53]
	s_ashr_i32 s1, s3, 3
	s_and_b32 s0, s7, 0x7000
	s_and_b32 s1, s1, -8
	s_add_i32 s0, s0, s1
	s_or_b32 s0, s0, s6
	s_ashr_i32 s1, s0, 31
	s_add_i32 s3, s3, s2
	s_add_i32 s7, s7, s8
	v_mov_b32_e32 v42, 0
	s_and_saveexec_b64 s[4:5], vcc
	v_lshl_add_u64 v[54:55], s[0:1], 0, v[16:17]
	v_lshl_add_u64 v[54:55], v[54:55], 4, v[20:21]
	global_load_dword v42, v[54:55], off
	s_or_b64 exec, exec, s[4:5]
	s_lshl_b64 s[4:5], s[0:1], 11
	v_lshl_add_u64 v[54:55], v[22:23], 0, s[4:5]
	global_load_dwordx4 v[44:47], v[54:55], off
	global_load_dwordx4 v[48:51], v[54:55], off offset:1024
	s_lshl_b64 s[4:5], s[0:1], 12
	v_lshl_add_u64 v[52:53], v[18:19], 0, s[4:5]
	global_store_dwordx4 v[82:83], v[64:67], off
	global_store_dwordx4 v[82:83], v[68:71], off offset:16
	global_store_dwordx4 v[82:83], v[72:75], off offset:2048
	global_store_dwordx4 v[82:83], v[76:79], off offset:2064
	s_waitcnt vmcnt(11)
	ds_bpermute_b32 v56, v24, v31
	s_waitcnt lgkmcnt(0)
	v_add_f32_e32 v31, v31, v56
	ds_bpermute_b32 v56, v25, v31
	s_waitcnt lgkmcnt(0)
	v_add_f32_e32 v31, v31, v56
	ds_bpermute_b32 v56, v26, v31
	s_waitcnt lgkmcnt(0)
	v_add_f32_e32 v31, v31, v56
	ds_bpermute_b32 v56, v27, v31
	s_waitcnt lgkmcnt(0)
	v_add_f32_e32 v31, v31, v56
	ds_bpermute_b32 v56, v28, v31
	s_waitcnt lgkmcnt(0)
	v_add_f32_e32 v31, v31, v56
	ds_bpermute_b32 v56, v29, v31
	s_waitcnt lgkmcnt(0)
	v_add_f32_e32 v31, v31, v56
	v_fmamk_f32 v31, v31, 0x3a800000, v30
	v_rsq_f32_e32 v80, v31
	v_mov_b32_e32 v81, v17
	v_lshlrev_b32_e32 v56, 16, v32
	v_and_b32_e32 v57, 0xffff0000, v32
	v_lshlrev_b32_e32 v58, 16, v33
	v_and_b32_e32 v59, 0xffff0000, v33
	v_lshlrev_b32_e32 v60, 16, v34
	v_and_b32_e32 v61, 0xffff0000, v34
	v_lshlrev_b32_e32 v62, 16, v35
	v_and_b32_e32 v63, 0xffff0000, v35
	v_pk_mul_f32 v[56:57], v[80:81], v[56:57] op_sel_hi:[0,1]
	v_pk_mul_f32 v[58:59], v[80:81], v[58:59] op_sel_hi:[0,1]
	v_pk_mul_f32 v[60:61], v[80:81], v[60:61] op_sel_hi:[0,1]
	v_pk_mul_f32 v[62:63], v[80:81], v[62:63] op_sel_hi:[0,1]
	v_pk_mul_f32 v[64:65], v[4:5], v[56:57]
	v_pk_mul_f32 v[66:67], v[6:7], v[58:59]
	v_pk_mul_f32 v[68:69], v[0:1], v[60:61]
	v_pk_mul_f32 v[70:71], v[2:3], v[62:63]
	v_lshlrev_b32_e32 v56, 16, v36
	v_and_b32_e32 v57, 0xffff0000, v36
	v_lshlrev_b32_e32 v58, 16, v37
	v_and_b32_e32 v59, 0xffff0000, v37
	v_lshlrev_b32_e32 v60, 16, v38
	v_and_b32_e32 v61, 0xffff0000, v38
	v_lshlrev_b32_e32 v62, 16, v39
	v_and_b32_e32 v63, 0xffff0000, v39
	v_pk_mul_f32 v[56:57], v[80:81], v[56:57] op_sel_hi:[0,1]
	v_pk_mul_f32 v[58:59], v[80:81], v[58:59] op_sel_hi:[0,1]
	v_pk_mul_f32 v[60:61], v[80:81], v[60:61] op_sel_hi:[0,1]
	v_pk_mul_f32 v[62:63], v[80:81], v[62:63] op_sel_hi:[0,1]
	v_pk_mul_f32 v[72:73], v[12:13], v[56:57]
	v_pk_mul_f32 v[74:75], v[14:15], v[58:59]
	v_pk_mul_f32 v[76:77], v[8:9], v[60:61]
	v_pk_mul_f32 v[78:79], v[10:11], v[62:63]
	v_mov_b64_e32 v[82:83], v[40:41]
	s_ashr_i32 s1, s3, 3
	s_and_b32 s0, s7, 0x7000
	s_and_b32 s1, s1, -8
	s_add_i32 s0, s0, s1
	s_or_b32 s0, s0, s6
	s_ashr_i32 s1, s0, 31
	s_add_i32 s3, s3, s2
	s_add_i32 s7, s7, s8
	v_mov_b32_e32 v31, 0
	s_and_saveexec_b64 s[4:5], vcc
	v_lshl_add_u64 v[54:55], s[0:1], 0, v[16:17]
	v_lshl_add_u64 v[54:55], v[54:55], 4, v[20:21]
	global_load_dword v31, v[54:55], off
	s_or_b64 exec, exec, s[4:5]
	s_lshl_b64 s[4:5], s[0:1], 11
	v_lshl_add_u64 v[54:55], v[22:23], 0, s[4:5]
	global_load_dwordx4 v[32:35], v[54:55], off
	global_load_dwordx4 v[36:39], v[54:55], off offset:1024
	s_lshl_b64 s[4:5], s[0:1], 12
	v_lshl_add_u64 v[40:41], v[18:19], 0, s[4:5]
	global_store_dwordx4 v[82:83], v[64:67], off
	global_store_dwordx4 v[82:83], v[68:71], off offset:16
	global_store_dwordx4 v[82:83], v[72:75], off offset:2048
	global_store_dwordx4 v[82:83], v[76:79], off offset:2064
	s_waitcnt vmcnt(11)
; __device__ __forceinline__ float bflo(unsigned w) { return __uint_as_float(w << 16); }
; __device__ __forceinline__ float bfhi(unsigned w) { return __uint_as_float(w & 0xffff0000u); }
; #define ssq ((float*)(WSPTR() + WS_SSQ))
; __device__ __forceinline__ void final_norm(const Args& a, int G, int vb) {
;     ...
;     for (int mi = gw; mi < NT; mi += NGW) {
;         const int m = XCD_ROW(mi);
;         float s = (lane < 16) ? ssq[((size_t)(lane >> 2) * NT + m) * 4 + (lane & 3)] : 0.f; s = wave_sum(s);
;         const float rs = __builtin_amdgcn_rsqf(s * (1.0f / 1024.0f) + 1e-6f);
;         const u32x4* xr = (const u32x4*)(xb + (size_t)m * DM) + lane; f32x4* orow = (f32x4*)(out + (size_t)m * DM) + 2 * lane;
; #pragma unroll
;         for (int j = 0; j < 2; ++j) { const u32x4 w = xr[64 * j];
;             orow[128 * j] = (f32x4){bflo(w.x), bfhi(w.x), bflo(w.y), bfhi(w.y)} * rs * gv[j][0];
;             orow[128 * j + 1] = (f32x4){bflo(w.z), bfhi(w.z), bflo(w.w), bfhi(w.w)} * rs * gv[j][1]; }
;     }
	ds_bpermute_b32 v56, v24, v42
	s_waitcnt lgkmcnt(0)
	v_add_f32_e32 v42, v42, v56
	ds_bpermute_b32 v56, v25, v42
	s_waitcnt lgkmcnt(0)
	v_add_f32_e32 v42, v42, v56
	ds_bpermute_b32 v56, v26, v42
	s_waitcnt lgkmcnt(0)
	v_add_f32_e32 v42, v42, v56
	ds_bpermute_b32 v56, v27, v42
	s_waitcnt lgkmcnt(0)
	v_add_f32_e32 v42, v42, v56
	ds_bpermute_b32 v56, v28, v42
	s_waitcnt lgkmcnt(0)
	v_add_f32_e32 v42, v42, v56
	ds_bpermute_b32 v56, v29, v42
	s_waitcnt lgkmcnt(0)
	v_add_f32_e32 v42, v42, v56
	v_fmamk_f32 v42, v42, 0x3a800000, v30
	v_rsq_f32_e32 v80, v42
	v_mov_b32_e32 v81, v17
	v_lshlrev_b32_e32 v56, 16, v44
	v_and_b32_e32 v57, 0xffff0000, v44
	v_lshlrev_b32_e32 v58, 16, v45
	v_and_b32_e32 v59, 0xffff0000, v45
	v_lshlrev_b32_e32 v60, 16, v46
	v_and_b32_e32 v61, 0xffff0000, v46
	v_lshlrev_b32_e32 v62, 16, v47
	v_and_b32_e32 v63, 0xffff0000, v47
	v_pk_mul_f32 v[56:57], v[80:81], v[56:57] op_sel_hi:[0,1]
	v_pk_mul_f32 v[58:59], v[80:81], v[58:59] op_sel_hi:[0,1]
	v_pk_mul_f32 v[60:61], v[80:81], v[60:61] op_sel_hi:[0,1]
	v_pk_mul_f32 v[62:63], v[80:81], v[62:63] op_sel_hi:[0,1]
	v_pk_mul_f32 v[64:65], v[4:5], v[56:57]
	v_pk_mul_f32 v[66:67], v[6:7], v[58:59]
	v_pk_mul_f32 v[68:69], v[0:1], v[60:61]
	v_pk_mul_f32 v[70:71], v[2:3], v[62:63]
	v_lshlrev_b32_e32 v56, 16, v48
	v_and_b32_e32 v57, 0xffff0000, v48
	v_lshlrev_b32_e32 v58, 16, v49
	v_and_b32_e32 v59, 0xffff0000, v49
	v_lshlrev_b32_e32 v60, 16, v50
	v_and_b32_e32 v61, 0xffff0000, v50
	v_lshlrev_b32_e32 v62, 16, v51
	v_and_b32_e32 v63, 0xffff0000, v51
	v_pk_mul_f32 v[56:57], v[80:81], v[56:57] op_sel_hi:[0,1]
	v_pk_mul_f32 v[58:59], v[80:81], v[58:59] op_sel_hi:[0,1]
	v_pk_mul_f32 v[60:61], v[80:81], v[60:61] op_sel_hi:[0,1]
	v_pk_mul_f32 v[62:63], v[80:81], v[62:63] op_sel_hi:[0,1]
	v_pk_mul_f32 v[72:73], v[12:13], v[56:57]
	v_pk_mul_f32 v[74:75], v[14:15], v[58:59]
	v_pk_mul_f32 v[76:77], v[8:9], v[60:61]
	v_pk_mul_f32 v[78:79], v[10:11], v[62:63]
	v_mov_b64_e32 v[82:83], v[52:53]
	s_ashr_i32 s1, s3, 3
	s_and_b32 s0, s7, 0x7000
	s_and_b32 s1, s1, -8
	s_add_i32 s0, s0, s1
	s_or_b32 s0, s0, s6
	s_ashr_i32 s1, s0, 31
	s_add_i32 s3, s3, s2
	s_add_i32 s7, s7, s8
	v_mov_b32_e32 v42, 0
	s_and_saveexec_b64 s[4:5], vcc
	v_lshl_add_u64 v[54:55], s[0:1], 0, v[16:17]
	v_lshl_add_u64 v[54:55], v[54:55], 4, v[20:21]
	global_load_dword v42, v[54:55], off
	s_or_b64 exec, exec, s[4:5]
	s_lshl_b64 s[4:5], s[0:1], 11
	v_lshl_add_u64 v[54:55], v[22:23], 0, s[4:5]
	global_load_dwordx4 v[44:47], v[54:55], off
	global_load_dwordx4 v[48:51], v[54:55], off offset:1024
	s_lshl_b64 s[4:5], s[0:1], 12
	v_lshl_add_u64 v[52:53], v[18:19], 0, s[4:5]
	global_store_dwordx4 v[82:83], v[64:67], off
	global_store_dwordx4 v[82:83], v[68:71], off offset:16
	global_store_dwordx4 v[82:83], v[72:75], off offset:2048
	global_store_dwordx4 v[82:83], v[76:79], off offset:2064
	s_waitcnt vmcnt(11)
	ds_bpermute_b32 v56, v24, v31
	s_waitcnt lgkmcnt(0)
	v_add_f32_e32 v31, v31, v56
	ds_bpermute_b32 v56, v25, v31
	s_waitcnt lgkmcnt(0)
	v_add_f32_e32 v31, v31, v56
	ds_bpermute_b32 v56, v26, v31
	s_waitcnt lgkmcnt(0)
	v_add_f32_e32 v31, v31, v56
	ds_bpermute_b32 v56, v27, v31
	s_waitcnt lgkmcnt(0)
	v_add_f32_e32 v31, v31, v56
	ds_bpermute_b32 v56, v28, v31
	s_waitcnt lgkmcnt(0)
	v_add_f32_e32 v31, v31, v56
	ds_bpermute_b32 v56, v29, v31
	s_waitcnt lgkmcnt(0)
	v_add_f32_e32 v31, v31, v56
	v_fmamk_f32 v31, v31, 0x3a800000, v30
	v_rsq_f32_e32 v80, v31
	v_mov_b32_e32 v81, v17
	v_lshlrev_b32_e32 v56, 16, v32
	v_and_b32_e32 v57, 0xffff0000, v32
	v_lshlrev_b32_e32 v58, 16, v33
	v_and_b32_e32 v59, 0xffff0000, v33
	v_lshlrev_b32_e32 v60, 16, v34
	v_and_b32_e32 v61, 0xffff0000, v34
	v_lshlrev_b32_e32 v62, 16, v35
	v_and_b32_e32 v63, 0xffff0000, v35
	v_pk_mul_f32 v[56:57], v[80:81], v[56:57] op_sel_hi:[0,1]
	v_pk_mul_f32 v[58:59], v[80:81], v[58:59] op_sel_hi:[0,1]
	v_pk_mul_f32 v[60:61], v[80:81], v[60:61] op_sel_hi:[0,1]
	v_pk_mul_f32 v[62:63], v[80:81], v[62:63] op_sel_hi:[0,1]
	v_pk_mul_f32 v[64:65], v[4:5], v[56:57]
	v_pk_mul_f32 v[66:67], v[6:7], v[58:59]
	v_pk_mul_f32 v[68:69], v[0:1], v[60:61]
	v_pk_mul_f32 v[70:71], v[2:3], v[62:63]
	v_lshlrev_b32_e32 v56, 16, v36
	v_and_b32_e32 v57, 0xffff0000, v36
	v_lshlrev_b32_e32 v58, 16, v37
	v_and_b32_e32 v59, 0xffff0000, v37
	v_lshlrev_b32_e32 v60, 16, v38
	v_and_b32_e32 v61, 0xffff0000, v38
	v_lshlrev_b32_e32 v62, 16, v39
	v_and_b32_e32 v63, 0xffff0000, v39
	v_pk_mul_f32 v[56:57], v[80:81], v[56:57] op_sel_hi:[0,1]
	v_pk_mul_f32 v[58:59], v[80:81], v[58:59] op_sel_hi:[0,1]
	v_pk_mul_f32 v[60:61], v[80:81], v[60:61] op_sel_hi:[0,1]
	v_pk_mul_f32 v[62:63], v[80:81], v[62:63] op_sel_hi:[0,1]
	v_pk_mul_f32 v[72:73], v[12:13], v[56:57]
	v_pk_mul_f32 v[74:75], v[14:15], v[58:59]
	v_pk_mul_f32 v[76:77], v[8:9], v[60:61]
	v_pk_mul_f32 v[78:79], v[10:11], v[62:63]
	v_mov_b64_e32 v[82:83], v[40:41]
	s_ashr_i32 s1, s3, 3
	s_and_b32 s0, s7, 0x7000
	s_and_b32 s1, s1, -8
	s_add_i32 s0, s0, s1
	s_or_b32 s0, s0, s6
	s_ashr_i32 s1, s0, 31
	s_add_i32 s3, s3, s2
	s_add_i32 s7, s7, s8
	v_mov_b32_e32 v31, 0
	s_and_saveexec_b64 s[4:5], vcc
	v_lshl_add_u64 v[54:55], s[0:1], 0, v[16:17]
	v_lshl_add_u64 v[54:55], v[54:55], 4, v[20:21]
	global_load_dword v31, v[54:55], off
	s_or_b64 exec, exec, s[4:5]
	s_lshl_b64 s[4:5], s[0:1], 11
	v_lshl_add_u64 v[54:55], v[22:23], 0, s[4:5]
	global_load_dwordx4 v[32:35], v[54:55], off
	global_load_dwordx4 v[36:39], v[54:55], off offset:1024
	s_lshl_b64 s[4:5], s[0:1], 12
	v_lshl_add_u64 v[40:41], v[18:19], 0, s[4:5]
	global_store_dwordx4 v[82:83], v[64:67], off
	global_store_dwordx4 v[82:83], v[68:71], off offset:16
	global_store_dwordx4 v[82:83], v[72:75], off offset:2048
	global_store_dwordx4 v[82:83], v[76:79], off offset:2064
	s_waitcnt vmcnt(11)
; __device__ __forceinline__ float bflo(unsigned w) { return __uint_as_float(w << 16); }
; __device__ __forceinline__ float bfhi(unsigned w) { return __uint_as_float(w & 0xffff0000u); }
; #define ssq ((float*)(WSPTR() + WS_SSQ))
; __device__ __forceinline__ void final_norm(const Args& a, int G, int vb) {
;     ...
;     for (int mi = gw; mi < NT; mi += NGW) {
;         const int m = XCD_ROW(mi);
;         float s = (lane < 16) ? ssq[((size_t)(lane >> 2) * NT + m) * 4 + (lane & 3)] : 0.f; s = wave_sum(s);
;         const float rs = __builtin_amdgcn_rsqf(s * (1.0f / 1024.0f) + 1e-6f);
;         const u32x4* xr = (const u32x4*)(xb + (size_t)m * DM) + lane; f32x4* orow = (f32x4*)(out + (size_t)m * DM) + 2 * lane;
; #pragma unroll
;         for (int j = 0; j < 2; ++j) { const u32x4 w = xr[64 * j];
;             orow[128 * j] = (f32x4){bflo(w.x), bfhi(w.x), bflo(w.y), bfhi(w.y)} * rs * gv[j][0];
;             orow[128 * j + 1] = (f32x4){bflo(w.z), bfhi(w.z), bflo(w.w), bfhi(w.w)} * rs * gv[j][1]; }
;     }
	ds_bpermute_b32 v56, v24, v42
	s_waitcnt lgkmcnt(0)
	v_add_f32_e32 v42, v42, v56
	ds_bpermute_b32 v56, v25, v42
	s_waitcnt lgkmcnt(0)
	v_add_f32_e32 v42, v42, v56
	ds_bpermute_b32 v56, v26, v42
	s_waitcnt lgkmcnt(0)
	v_add_f32_e32 v42, v42, v56
	ds_bpermute_b32 v56, v27, v42
	s_waitcnt lgkmcnt(0)
	v_add_f32_e32 v42, v42, v56
	ds_bpermute_b32 v56, v28, v42
	s_waitcnt lgkmcnt(0)
	v_add_f32_e32 v42, v42, v56
	ds_bpermute_b32 v56, v29, v42
	s_waitcnt lgkmcnt(0)
	v_add_f32_e32 v42, v42, v56
	v_fmamk_f32 v42, v42, 0x3a800000, v30
	v_rsq_f32_e32 v80, v42
	v_mov_b32_e32 v81, v17
	v_lshlrev_b32_e32 v56, 16, v44
	v_and_b32_e32 v57, 0xffff0000, v44
	v_lshlrev_b32_e32 v58, 16, v45
	v_and_b32_e32 v59, 0xffff0000, v45
	v_lshlrev_b32_e32 v60, 16, v46
	v_and_b32_e32 v61, 0xffff0000, v46
	v_lshlrev_b32_e32 v62, 16, v47
	v_and_b32_e32 v63, 0xffff0000, v47
	v_pk_mul_f32 v[56:57], v[80:81], v[56:57] op_sel_hi:[0,1]
	v_pk_mul_f32 v[58:59], v[80:81], v[58:59] op_sel_hi:[0,1]
	v_pk_mul_f32 v[60:61], v[80:81], v[60:61] op_sel_hi:[0,1]
	v_pk_mul_f32 v[62:63], v[80:81], v[62:63] op_sel_hi:[0,1]
	v_pk_mul_f32 v[64:65], v[4:5], v[56:57]
	v_pk_mul_f32 v[66:67], v[6:7], v[58:59]
	v_pk_mul_f32 v[68:69], v[0:1], v[60:61]
	v_pk_mul_f32 v[70:71], v[2:3], v[62:63]
	v_lshlrev_b32_e32 v56, 16, v48
	v_and_b32_e32 v57, 0xffff0000, v48
	v_lshlrev_b32_e32 v58, 16, v49
	v_and_b32_e32 v59, 0xffff0000, v49
	v_lshlrev_b32_e32 v60, 16, v50
	v_and_b32_e32 v61, 0xffff0000, v50
	v_lshlrev_b32_e32 v62, 16, v51
	v_and_b32_e32 v63, 0xffff0000, v51
	v_pk_mul_f32 v[56:57], v[80:81], v[56:57] op_sel_hi:[0,1]
	v_pk_mul_f32 v[58:59], v[80:81], v[58:59] op_sel_hi:[0,1]
	v_pk_mul_f32 v[60:61], v[80:81], v[60:61] op_sel_hi:[0,1]
	v_pk_mul_f32 v[62:63], v[80:81], v[62:63] op_sel_hi:[0,1]
	v_pk_mul_f32 v[72:73], v[12:13], v[56:57]
	v_pk_mul_f32 v[74:75], v[14:15], v[58:59]
	v_pk_mul_f32 v[76:77], v[8:9], v[60:61]
	v_pk_mul_f32 v[78:79], v[10:11], v[62:63]
	v_mov_b64_e32 v[82:83], v[52:53]
	s_ashr_i32 s1, s3, 3
	s_and_b32 s0, s7, 0x7000
	s_and_b32 s1, s1, -8
	s_add_i32 s0, s0, s1
	s_or_b32 s0, s0, s6
	s_ashr_i32 s1, s0, 31
	s_add_i32 s3, s3, s2
	s_add_i32 s7, s7, s8
	v_mov_b32_e32 v42, 0
	s_and_saveexec_b64 s[4:5], vcc
	v_lshl_add_u64 v[54:55], s[0:1], 0, v[16:17]
	v_lshl_add_u64 v[54:55], v[54:55], 4, v[20:21]
	global_load_dword v42, v[54:55], off
	s_or_b64 exec, exec, s[4:5]
	s_lshl_b64 s[4:5], s[0:1], 11
	v_lshl_add_u64 v[54:55], v[22:23], 0, s[4:5]
	global_load_dwordx4 v[44:47], v[54:55], off
	global_load_dwordx4 v[48:51], v[54:55], off offset:1024
	s_lshl_b64 s[4:5], s[0:1], 12
	v_lshl_add_u64 v[52:53], v[18:19], 0, s[4:5]
	global_store_dwordx4 v[82:83], v[64:67], off
	global_store_dwordx4 v[82:83], v[68:71], off offset:16
	global_store_dwordx4 v[82:83], v[72:75], off offset:2048
	global_store_dwordx4 v[82:83], v[76:79], off offset:2064
	s_waitcnt vmcnt(11)
	ds_bpermute_b32 v56, v24, v31
	s_waitcnt lgkmcnt(0)
	v_add_f32_e32 v31, v31, v56
	ds_bpermute_b32 v56, v25, v31
	s_waitcnt lgkmcnt(0)
	v_add_f32_e32 v31, v31, v56
	ds_bpermute_b32 v56, v26, v31
	s_waitcnt lgkmcnt(0)
	v_add_f32_e32 v31, v31, v56
	ds_bpermute_b32 v56, v27, v31
	s_waitcnt lgkmcnt(0)
	v_add_f32_e32 v31, v31, v56
	ds_bpermute_b32 v56, v28, v31
	s_waitcnt lgkmcnt(0)
	v_add_f32_e32 v31, v31, v56
	ds_bpermute_b32 v56, v29, v31
	s_waitcnt lgkmcnt(0)
	v_add_f32_e32 v31, v31, v56
	v_fmamk_f32 v31, v31, 0x3a800000, v30
	v_rsq_f32_e32 v80, v31
	v_mov_b32_e32 v81, v17
	v_lshlrev_b32_e32 v56, 16, v32
	v_and_b32_e32 v57, 0xffff0000, v32
	v_lshlrev_b32_e32 v58, 16, v33
	v_and_b32_e32 v59, 0xffff0000, v33
	v_lshlrev_b32_e32 v60, 16, v34
	v_and_b32_e32 v61, 0xffff0000, v34
	v_lshlrev_b32_e32 v62, 16, v35
	v_and_b32_e32 v63, 0xffff0000, v35
	v_pk_mul_f32 v[56:57], v[80:81], v[56:57] op_sel_hi:[0,1]
	v_pk_mul_f32 v[58:59], v[80:81], v[58:59] op_sel_hi:[0,1]
	v_pk_mul_f32 v[60:61], v[80:81], v[60:61] op_sel_hi:[0,1]
	v_pk_mul_f32 v[62:63], v[80:81], v[62:63] op_sel_hi:[0,1]
	v_pk_mul_f32 v[64:65], v[4:5], v[56:57]
	v_pk_mul_f32 v[66:67], v[6:7], v[58:59]
	v_pk_mul_f32 v[68:69], v[0:1], v[60:61]
	v_pk_mul_f32 v[70:71], v[2:3], v[62:63]
	v_lshlrev_b32_e32 v56, 16, v36
	v_and_b32_e32 v57, 0xffff0000, v36
	v_lshlrev_b32_e32 v58, 16, v37
	v_and_b32_e32 v59, 0xffff0000, v37
	v_lshlrev_b32_e32 v60, 16, v38
	v_and_b32_e32 v61, 0xffff0000, v38
	v_lshlrev_b32_e32 v62, 16, v39
	v_and_b32_e32 v63, 0xffff0000, v39
	v_pk_mul_f32 v[56:57], v[80:81], v[56:57] op_sel_hi:[0,1]
	v_pk_mul_f32 v[58:59], v[80:81], v[58:59] op_sel_hi:[0,1]
	v_pk_mul_f32 v[60:61], v[80:81], v[60:61] op_sel_hi:[0,1]
	v_pk_mul_f32 v[62:63], v[80:81], v[62:63] op_sel_hi:[0,1]
	v_pk_mul_f32 v[72:73], v[12:13], v[56:57]
	v_pk_mul_f32 v[74:75], v[14:15], v[58:59]
	v_pk_mul_f32 v[76:77], v[8:9], v[60:61]
	v_pk_mul_f32 v[78:79], v[10:11], v[62:63]
	v_mov_b64_e32 v[82:83], v[40:41]
	s_ashr_i32 s1, s3, 3
	s_and_b32 s0, s7, 0x7000
	s_and_b32 s1, s1, -8
	s_add_i32 s0, s0, s1
	s_or_b32 s0, s0, s6
	s_ashr_i32 s1, s0, 31
	s_add_i32 s3, s3, s2
	s_add_i32 s7, s7, s8
	v_mov_b32_e32 v31, 0
	s_and_saveexec_b64 s[4:5], vcc
	v_lshl_add_u64 v[54:55], s[0:1], 0, v[16:17]
	v_lshl_add_u64 v[54:55], v[54:55], 4, v[20:21]
	global_load_dword v31, v[54:55], off
	s_or_b64 exec, exec, s[4:5]
	s_lshl_b64 s[4:5], s[0:1], 11
	v_lshl_add_u64 v[54:55], v[22:23], 0, s[4:5]
	global_load_dwordx4 v[32:35], v[54:55], off
	global_load_dwordx4 v[36:39], v[54:55], off offset:1024
	s_lshl_b64 s[4:5], s[0:1], 12
	v_lshl_add_u64 v[40:41], v[18:19], 0, s[4:5]
	global_store_dwordx4 v[82:83], v[64:67], off
	global_store_dwordx4 v[82:83], v[68:71], off offset:16
	global_store_dwordx4 v[82:83], v[72:75], off offset:2048
	global_store_dwordx4 v[82:83], v[76:79], off offset:2064
	s_waitcnt vmcnt(11)
; __device__ __forceinline__ float bflo(unsigned w) { return __uint_as_float(w << 16); }
; __device__ __forceinline__ float bfhi(unsigned w) { return __uint_as_float(w & 0xffff0000u); }
; #define ssq ((float*)(WSPTR() + WS_SSQ))
; __device__ __forceinline__ void final_norm(const Args& a, int G, int vb) {
;     ...
;     for (int mi = gw; mi < NT; mi += NGW) {
;         const int m = XCD_ROW(mi);
;         float s = (lane < 16) ? ssq[((size_t)(lane >> 2) * NT + m) * 4 + (lane & 3)] : 0.f; s = wave_sum(s);
;         const float rs = __builtin_amdgcn_rsqf(s * (1.0f / 1024.0f) + 1e-6f);
;         const u32x4* xr = (const u32x4*)(xb + (size_t)m * DM) + lane; f32x4* orow = (f32x4*)(out + (size_t)m * DM) + 2 * lane;
; #pragma unroll
;         for (int j = 0; j < 2; ++j) { const u32x4 w = xr[64 * j];
;             orow[128 * j] = (f32x4){bflo(w.x), bfhi(w.x), bflo(w.y), bfhi(w.y)} * rs * gv[j][0];
;             orow[128 * j + 1] = (f32x4){bflo(w.z), bfhi(w.z), bflo(w.w), bfhi(w.w)} * rs * gv[j][1]; }
;     }
	ds_bpermute_b32 v56, v24, v42
	s_waitcnt lgkmcnt(0)
	v_add_f32_e32 v42, v42, v56
	ds_bpermute_b32 v56, v25, v42
	s_waitcnt lgkmcnt(0)
	v_add_f32_e32 v42, v42, v56
	ds_bpermute_b32 v56, v26, v42
	s_waitcnt lgkmcnt(0)
	v_add_f32_e32 v42, v42, v56
	ds_bpermute_b32 v56, v27, v42
	s_waitcnt lgkmcnt(0)
	v_add_f32_e32 v42, v42, v56
	ds_bpermute_b32 v56, v28, v42
	s_waitcnt lgkmcnt(0)
	v_add_f32_e32 v42, v42, v56
	ds_bpermute_b32 v56, v29, v42
	s_waitcnt lgkmcnt(0)
	v_add_f32_e32 v42, v42, v56
	v_fmamk_f32 v42, v42, 0x3a800000, v30
	v_rsq_f32_e32 v80, v42
	v_mov_b32_e32 v81, v17
	v_lshlrev_b32_e32 v56, 16, v44
	v_and_b32_e32 v57, 0xffff0000, v44
	v_lshlrev_b32_e32 v58, 16, v45
	v_and_b32_e32 v59, 0xffff0000, v45
	v_lshlrev_b32_e32 v60, 16, v46
	v_and_b32_e32 v61, 0xffff0000, v46
	v_lshlrev_b32_e32 v62, 16, v47
	v_and_b32_e32 v63, 0xffff0000, v47
	v_pk_mul_f32 v[56:57], v[80:81], v[56:57] op_sel_hi:[0,1]
	v_pk_mul_f32 v[58:59], v[80:81], v[58:59] op_sel_hi:[0,1]
	v_pk_mul_f32 v[60:61], v[80:81], v[60:61] op_sel_hi:[0,1]
	v_pk_mul_f32 v[62:63], v[80:81], v[62:63] op_sel_hi:[0,1]
	v_pk_mul_f32 v[64:65], v[4:5], v[56:57]
	v_pk_mul_f32 v[66:67], v[6:7], v[58:59]
	v_pk_mul_f32 v[68:69], v[0:1], v[60:61]
	v_pk_mul_f32 v[70:71], v[2:3], v[62:63]
	v_lshlrev_b32_e32 v56, 16, v48
	v_and_b32_e32 v57, 0xffff0000, v48
	v_lshlrev_b32_e32 v58, 16, v49
	v_and_b32_e32 v59, 0xffff0000, v49
	v_lshlrev_b32_e32 v60, 16, v50
	v_and_b32_e32 v61, 0xffff0000, v50
	v_lshlrev_b32_e32 v62, 16, v51
	v_and_b32_e32 v63, 0xffff0000, v51
	v_pk_mul_f32 v[56:57], v[80:81], v[56:57] op_sel_hi:[0,1]
	v_pk_mul_f32 v[58:59], v[80:81], v[58:59] op_sel_hi:[0,1]
	v_pk_mul_f32 v[60:61], v[80:81], v[60:61] op_sel_hi:[0,1]
	v_pk_mul_f32 v[62:63], v[80:81], v[62:63] op_sel_hi:[0,1]
	v_pk_mul_f32 v[72:73], v[12:13], v[56:57]
	v_pk_mul_f32 v[74:75], v[14:15], v[58:59]
	v_pk_mul_f32 v[76:77], v[8:9], v[60:61]
	v_pk_mul_f32 v[78:79], v[10:11], v[62:63]
	v_mov_b64_e32 v[82:83], v[52:53]
	s_ashr_i32 s1, s3, 3
	s_and_b32 s0, s7, 0x7000
	s_and_b32 s1, s1, -8
	s_add_i32 s0, s0, s1
	s_or_b32 s0, s0, s6
	s_ashr_i32 s1, s0, 31
	s_add_i32 s3, s3, s2
	s_add_i32 s7, s7, s8
	v_mov_b32_e32 v42, 0
	s_and_saveexec_b64 s[4:5], vcc
	v_lshl_add_u64 v[54:55], s[0:1], 0, v[16:17]
	v_lshl_add_u64 v[54:55], v[54:55], 4, v[20:21]
	global_load_dword v42, v[54:55], off
	s_or_b64 exec, exec, s[4:5]
	s_lshl_b64 s[4:5], s[0:1], 11
	v_lshl_add_u64 v[54:55], v[22:23], 0, s[4:5]
	global_load_dwordx4 v[44:47], v[54:55], off
	global_load_dwordx4 v[48:51], v[54:55], off offset:1024
	s_lshl_b64 s[4:5], s[0:1], 12
	v_lshl_add_u64 v[52:53], v[18:19], 0, s[4:5]
	global_store_dwordx4 v[82:83], v[64:67], off
	global_store_dwordx4 v[82:83], v[68:71], off offset:16
	global_store_dwordx4 v[82:83], v[72:75], off offset:2048
	global_store_dwordx4 v[82:83], v[76:79], off offset:2064
	s_waitcnt vmcnt(11)
	ds_bpermute_b32 v56, v24, v31
	s_waitcnt lgkmcnt(0)
	v_add_f32_e32 v31, v31, v56
	ds_bpermute_b32 v56, v25, v31
	s_waitcnt lgkmcnt(0)
	v_add_f32_e32 v31, v31, v56
	ds_bpermute_b32 v56, v26, v31
	s_waitcnt lgkmcnt(0)
	v_add_f32_e32 v31, v31, v56
	ds_bpermute_b32 v56, v27, v31
	s_waitcnt lgkmcnt(0)
	v_add_f32_e32 v31, v31, v56
	ds_bpermute_b32 v56, v28, v31
	s_waitcnt lgkmcnt(0)
	v_add_f32_e32 v31, v31, v56
	ds_bpermute_b32 v56, v29, v31
	s_waitcnt lgkmcnt(0)
	v_add_f32_e32 v31, v31, v56
	v_fmamk_f32 v31, v31, 0x3a800000, v30
	v_rsq_f32_e32 v80, v31
	v_mov_b32_e32 v81, v17
	v_lshlrev_b32_e32 v56, 16, v32
	v_and_b32_e32 v57, 0xffff0000, v32
	v_lshlrev_b32_e32 v58, 16, v33
	v_and_b32_e32 v59, 0xffff0000, v33
	v_lshlrev_b32_e32 v60, 16, v34
	v_and_b32_e32 v61, 0xffff0000, v34
	v_lshlrev_b32_e32 v62, 16, v35
	v_and_b32_e32 v63, 0xffff0000, v35
	v_pk_mul_f32 v[56:57], v[80:81], v[56:57] op_sel_hi:[0,1]
	v_pk_mul_f32 v[58:59], v[80:81], v[58:59] op_sel_hi:[0,1]
	v_pk_mul_f32 v[60:61], v[80:81], v[60:61] op_sel_hi:[0,1]
	v_pk_mul_f32 v[62:63], v[80:81], v[62:63] op_sel_hi:[0,1]
	v_pk_mul_f32 v[64:65], v[4:5], v[56:57]
	v_pk_mul_f32 v[66:67], v[6:7], v[58:59]
	v_pk_mul_f32 v[68:69], v[0:1], v[60:61]
	v_pk_mul_f32 v[70:71], v[2:3], v[62:63]
	v_lshlrev_b32_e32 v56, 16, v36
	v_and_b32_e32 v57, 0xffff0000, v36
	v_lshlrev_b32_e32 v58, 16, v37
	v_and_b32_e32 v59, 0xffff0000, v37
	v_lshlrev_b32_e32 v60, 16, v38
	v_and_b32_e32 v61, 0xffff0000, v38
	v_lshlrev_b32_e32 v62, 16, v39
	v_and_b32_e32 v63, 0xffff0000, v39
	v_pk_mul_f32 v[56:57], v[80:81], v[56:57] op_sel_hi:[0,1]
	v_pk_mul_f32 v[58:59], v[80:81], v[58:59] op_sel_hi:[0,1]
	v_pk_mul_f32 v[60:61], v[80:81], v[60:61] op_sel_hi:[0,1]
	v_pk_mul_f32 v[62:63], v[80:81], v[62:63] op_sel_hi:[0,1]
	v_pk_mul_f32 v[72:73], v[12:13], v[56:57]
	v_pk_mul_f32 v[74:75], v[14:15], v[58:59]
	v_pk_mul_f32 v[76:77], v[8:9], v[60:61]
	v_pk_mul_f32 v[78:79], v[10:11], v[62:63]
	v_mov_b64_e32 v[82:83], v[40:41]
	s_ashr_i32 s1, s3, 3
	s_and_b32 s0, s7, 0x7000
	s_and_b32 s1, s1, -8
	s_add_i32 s0, s0, s1
	s_or_b32 s0, s0, s6
	s_ashr_i32 s1, s0, 31
	s_add_i32 s3, s3, s2
	s_add_i32 s7, s7, s8
	v_mov_b32_e32 v31, 0
	s_and_saveexec_b64 s[4:5], vcc
	v_lshl_add_u64 v[54:55], s[0:1], 0, v[16:17]
	v_lshl_add_u64 v[54:55], v[54:55], 4, v[20:21]
	global_load_dword v31, v[54:55], off
	s_or_b64 exec, exec, s[4:5]
	s_lshl_b64 s[4:5], s[0:1], 11
	v_lshl_add_u64 v[54:55], v[22:23], 0, s[4:5]
	global_load_dwordx4 v[32:35], v[54:55], off
	global_load_dwordx4 v[36:39], v[54:55], off offset:1024
	s_lshl_b64 s[4:5], s[0:1], 12
	v_lshl_add_u64 v[40:41], v[18:19], 0, s[4:5]
	global_store_dwordx4 v[82:83], v[64:67], off
	global_store_dwordx4 v[82:83], v[68:71], off offset:16
	global_store_dwordx4 v[82:83], v[72:75], off offset:2048
	global_store_dwordx4 v[82:83], v[76:79], off offset:2064
	s_waitcnt vmcnt(11)
; __device__ __forceinline__ float bflo(unsigned w) { return __uint_as_float(w << 16); }
; __device__ __forceinline__ float bfhi(unsigned w) { return __uint_as_float(w & 0xffff0000u); }
; #define ssq ((float*)(WSPTR() + WS_SSQ))
; __device__ __forceinline__ void final_norm(const Args& a, int G, int vb) {
;     ...
;     for (int mi = gw; mi < NT; mi += NGW) {
;         const int m = XCD_ROW(mi);
;         float s = (lane < 16) ? ssq[((size_t)(lane >> 2) * NT + m) * 4 + (lane & 3)] : 0.f; s = wave_sum(s);
;         const float rs = __builtin_amdgcn_rsqf(s * (1.0f / 1024.0f) + 1e-6f);
;         const u32x4* xr = (const u32x4*)(xb + (size_t)m * DM) + lane; f32x4* orow = (f32x4*)(out + (size_t)m * DM) + 2 * lane;
; #pragma unroll
;         for (int j = 0; j < 2; ++j) { const u32x4 w = xr[64 * j];
;             orow[128 * j] = (f32x4){bflo(w.x), bfhi(w.x), bflo(w.y), bfhi(w.y)} * rs * gv[j][0];
;             orow[128 * j + 1] = (f32x4){bflo(w.z), bfhi(w.z), bflo(w.w), bfhi(w.w)} * rs * gv[j][1]; }
;     }
	ds_bpermute_b32 v56, v24, v42
	s_waitcnt lgkmcnt(0)
	v_add_f32_e32 v42, v42, v56
	ds_bpermute_b32 v56, v25, v42
	s_waitcnt lgkmcnt(0)
	v_add_f32_e32 v42, v42, v56
	ds_bpermute_b32 v56, v26, v42
	s_waitcnt lgkmcnt(0)
	v_add_f32_e32 v42, v42, v56
	ds_bpermute_b32 v56, v27, v42
	s_waitcnt lgkmcnt(0)
	v_add_f32_e32 v42, v42, v56
	ds_bpermute_b32 v56, v28, v42
	s_waitcnt lgkmcnt(0)
	v_add_f32_e32 v42, v42, v56
	ds_bpermute_b32 v56, v29, v42
	s_waitcnt lgkmcnt(0)
	v_add_f32_e32 v42, v42, v56
	v_fmamk_f32 v42, v42, 0x3a800000, v30
	v_rsq_f32_e32 v80, v42
	v_mov_b32_e32 v81, v17
	v_lshlrev_b32_e32 v56, 16, v44
	v_and_b32_e32 v57, 0xffff0000, v44
	v_lshlrev_b32_e32 v58, 16, v45
	v_and_b32_e32 v59, 0xffff0000, v45
	v_lshlrev_b32_e32 v60, 16, v46
	v_and_b32_e32 v61, 0xffff0000, v46
	v_lshlrev_b32_e32 v62, 16, v47
	v_and_b32_e32 v63, 0xffff0000, v47
	v_pk_mul_f32 v[56:57], v[80:81], v[56:57] op_sel_hi:[0,1]
	v_pk_mul_f32 v[58:59], v[80:81], v[58:59] op_sel_hi:[0,1]
	v_pk_mul_f32 v[60:61], v[80:81], v[60:61] op_sel_hi:[0,1]
	v_pk_mul_f32 v[62:63], v[80:81], v[62:63] op_sel_hi:[0,1]
	v_pk_mul_f32 v[64:65], v[4:5], v[56:57]
	v_pk_mul_f32 v[66:67], v[6:7], v[58:59]
	v_pk_mul_f32 v[68:69], v[0:1], v[60:61]
	v_pk_mul_f32 v[70:71], v[2:3], v[62:63]
	v_lshlrev_b32_e32 v56, 16, v48
	v_and_b32_e32 v57, 0xffff0000, v48
	v_lshlrev_b32_e32 v58, 16, v49
	v_and_b32_e32 v59, 0xffff0000, v49
	v_lshlrev_b32_e32 v60, 16, v50
	v_and_b32_e32 v61, 0xffff0000, v50
	v_lshlrev_b32_e32 v62, 16, v51
	v_and_b32_e32 v63, 0xffff0000, v51
	v_pk_mul_f32 v[56:57], v[80:81], v[56:57] op_sel_hi:[0,1]
	v_pk_mul_f32 v[58:59], v[80:81], v[58:59] op_sel_hi:[0,1]
	v_pk_mul_f32 v[60:61], v[80:81], v[60:61] op_sel_hi:[0,1]
	v_pk_mul_f32 v[62:63], v[80:81], v[62:63] op_sel_hi:[0,1]
	v_pk_mul_f32 v[72:73], v[12:13], v[56:57]
	v_pk_mul_f32 v[74:75], v[14:15], v[58:59]
	v_pk_mul_f32 v[76:77], v[8:9], v[60:61]
	v_pk_mul_f32 v[78:79], v[10:11], v[62:63]
	v_mov_b64_e32 v[82:83], v[52:53]
	s_ashr_i32 s1, s3, 3
	s_and_b32 s0, s7, 0x7000
	s_and_b32 s1, s1, -8
	s_add_i32 s0, s0, s1
	s_or_b32 s0, s0, s6
	s_ashr_i32 s1, s0, 31
	s_add_i32 s3, s3, s2
	s_add_i32 s7, s7, s8
	v_mov_b32_e32 v42, 0
	s_and_saveexec_b64 s[4:5], vcc
	v_lshl_add_u64 v[54:55], s[0:1], 0, v[16:17]
	v_lshl_add_u64 v[54:55], v[54:55], 4, v[20:21]
	global_load_dword v42, v[54:55], off
	s_or_b64 exec, exec, s[4:5]
	s_lshl_b64 s[4:5], s[0:1], 11
	v_lshl_add_u64 v[54:55], v[22:23], 0, s[4:5]
	global_load_dwordx4 v[44:47], v[54:55], off
	global_load_dwordx4 v[48:51], v[54:55], off offset:1024
	s_lshl_b64 s[4:5], s[0:1], 12
	v_lshl_add_u64 v[52:53], v[18:19], 0, s[4:5]
	global_store_dwordx4 v[82:83], v[64:67], off
	global_store_dwordx4 v[82:83], v[68:71], off offset:16
	global_store_dwordx4 v[82:83], v[72:75], off offset:2048
	global_store_dwordx4 v[82:83], v[76:79], off offset:2064
	s_waitcnt vmcnt(11)
	ds_bpermute_b32 v56, v24, v31
	s_waitcnt lgkmcnt(0)
	v_add_f32_e32 v31, v31, v56
	ds_bpermute_b32 v56, v25, v31
	s_waitcnt lgkmcnt(0)
	v_add_f32_e32 v31, v31, v56
	ds_bpermute_b32 v56, v26, v31
	s_waitcnt lgkmcnt(0)
	v_add_f32_e32 v31, v31, v56
	ds_bpermute_b32 v56, v27, v31
	s_waitcnt lgkmcnt(0)
	v_add_f32_e32 v31, v31, v56
	ds_bpermute_b32 v56, v28, v31
	s_waitcnt lgkmcnt(0)
	v_add_f32_e32 v31, v31, v56
	ds_bpermute_b32 v56, v29, v31
	s_waitcnt lgkmcnt(0)
; __device__ __forceinline__ float bflo(unsigned w) { return __uint_as_float(w << 16); }
; __device__ __forceinline__ float bfhi(unsigned w) { return __uint_as_float(w & 0xffff0000u); }
; #define ssq ((float*)(WSPTR() + WS_SSQ))
; __device__ __forceinline__ void final_norm(const Args& a, int G, int vb) {
;     ...
;     for (int mi = gw; mi < NT; mi += NGW) {
;         const int m = XCD_ROW(mi);
;         float s = (lane < 16) ? ssq[((size_t)(lane >> 2) * NT + m) * 4 + (lane & 3)] : 0.f; s = wave_sum(s);
;         const float rs = __builtin_amdgcn_rsqf(s * (1.0f / 1024.0f) + 1e-6f);
;         const u32x4* xr = (const u32x4*)(xb + (size_t)m * DM) + lane; f32x4* orow = (f32x4*)(out + (size_t)m * DM) + 2 * lane;
; #pragma unroll
;         for (int j = 0; j < 2; ++j) { const u32x4 w = xr[64 * j];
;             orow[128 * j] = (f32x4){bflo(w.x), bfhi(w.x), bflo(w.y), bfhi(w.y)} * rs * gv[j][0];
;             orow[128 * j + 1] = (f32x4){bflo(w.z), bfhi(w.z), bflo(w.w), bfhi(w.w)} * rs * gv[j][1]; }
;     }
	v_add_f32_e32 v31, v31, v56
	v_fmamk_f32 v31, v31, 0x3a800000, v30
	v_rsq_f32_e32 v80, v31
	v_mov_b32_e32 v81, v17
	v_lshlrev_b32_e32 v56, 16, v32
	v_and_b32_e32 v57, 0xffff0000, v32
	v_lshlrev_b32_e32 v58, 16, v33
	v_and_b32_e32 v59, 0xffff0000, v33
	v_lshlrev_b32_e32 v60, 16, v34
	v_and_b32_e32 v61, 0xffff0000, v34
	v_lshlrev_b32_e32 v62, 16, v35
	v_and_b32_e32 v63, 0xffff0000, v35
	v_pk_mul_f32 v[56:57], v[80:81], v[56:57] op_sel_hi:[0,1]
	v_pk_mul_f32 v[58:59], v[80:81], v[58:59] op_sel_hi:[0,1]
	v_pk_mul_f32 v[60:61], v[80:81], v[60:61] op_sel_hi:[0,1]
	v_pk_mul_f32 v[62:63], v[80:81], v[62:63] op_sel_hi:[0,1]
	v_pk_mul_f32 v[64:65], v[4:5], v[56:57]
	v_pk_mul_f32 v[66:67], v[6:7], v[58:59]
	v_pk_mul_f32 v[68:69], v[0:1], v[60:61]
	v_pk_mul_f32 v[70:71], v[2:3], v[62:63]
	v_lshlrev_b32_e32 v56, 16, v36
	v_and_b32_e32 v57, 0xffff0000, v36
	v_lshlrev_b32_e32 v58, 16, v37
	v_and_b32_e32 v59, 0xffff0000, v37
	v_lshlrev_b32_e32 v60, 16, v38
	v_and_b32_e32 v61, 0xffff0000, v38
	v_lshlrev_b32_e32 v62, 16, v39
	v_and_b32_e32 v63, 0xffff0000, v39
	v_pk_mul_f32 v[56:57], v[80:81], v[56:57] op_sel_hi:[0,1]
	v_pk_mul_f32 v[58:59], v[80:81], v[58:59] op_sel_hi:[0,1]
	v_pk_mul_f32 v[60:61], v[80:81], v[60:61] op_sel_hi:[0,1]
	v_pk_mul_f32 v[62:63], v[80:81], v[62:63] op_sel_hi:[0,1]
	v_pk_mul_f32 v[72:73], v[12:13], v[56:57]
	v_pk_mul_f32 v[74:75], v[14:15], v[58:59]
	v_pk_mul_f32 v[76:77], v[8:9], v[60:61]
	v_pk_mul_f32 v[78:79], v[10:11], v[62:63]
	v_mov_b64_e32 v[82:83], v[40:41]
	global_store_dwordx4 v[82:83], v[64:67], off
	global_store_dwordx4 v[82:83], v[68:71], off offset:16
	global_store_dwordx4 v[82:83], v[72:75], off offset:2048
	global_store_dwordx4 v[82:83], v[76:79], off offset:2064
	s_waitcnt vmcnt(8)
	ds_bpermute_b32 v56, v24, v42
	s_waitcnt lgkmcnt(0)
	v_add_f32_e32 v42, v42, v56
	ds_bpermute_b32 v56, v25, v42
	s_waitcnt lgkmcnt(0)
	v_add_f32_e32 v42, v42, v56
	ds_bpermute_b32 v56, v26, v42
	s_waitcnt lgkmcnt(0)
	v_add_f32_e32 v42, v42, v56
	ds_bpermute_b32 v56, v27, v42
	s_waitcnt lgkmcnt(0)
	v_add_f32_e32 v42, v42, v56
	ds_bpermute_b32 v56, v28, v42
	s_waitcnt lgkmcnt(0)
	v_add_f32_e32 v42, v42, v56
	ds_bpermute_b32 v56, v29, v42
	s_waitcnt lgkmcnt(0)
	v_add_f32_e32 v42, v42, v56
	v_fmamk_f32 v42, v42, 0x3a800000, v30
	v_rsq_f32_e32 v80, v42
	v_mov_b32_e32 v81, v17
	v_lshlrev_b32_e32 v56, 16, v44
	v_and_b32_e32 v57, 0xffff0000, v44
	v_lshlrev_b32_e32 v58, 16, v45
	v_and_b32_e32 v59, 0xffff0000, v45
	v_lshlrev_b32_e32 v60, 16, v46
	v_and_b32_e32 v61, 0xffff0000, v46
	v_lshlrev_b32_e32 v62, 16, v47
	v_and_b32_e32 v63, 0xffff0000, v47
	v_pk_mul_f32 v[56:57], v[80:81], v[56:57] op_sel_hi:[0,1]
	v_pk_mul_f32 v[58:59], v[80:81], v[58:59] op_sel_hi:[0,1]
	v_pk_mul_f32 v[60:61], v[80:81], v[60:61] op_sel_hi:[0,1]
	v_pk_mul_f32 v[62:63], v[80:81], v[62:63] op_sel_hi:[0,1]
	v_pk_mul_f32 v[64:65], v[4:5], v[56:57]
	v_pk_mul_f32 v[66:67], v[6:7], v[58:59]
	v_pk_mul_f32 v[68:69], v[0:1], v[60:61]
	v_pk_mul_f32 v[70:71], v[2:3], v[62:63]
	v_lshlrev_b32_e32 v56, 16, v48
	v_and_b32_e32 v57, 0xffff0000, v48
	v_lshlrev_b32_e32 v58, 16, v49
	v_and_b32_e32 v59, 0xffff0000, v49
	v_lshlrev_b32_e32 v60, 16, v50
	v_and_b32_e32 v61, 0xffff0000, v50
	v_lshlrev_b32_e32 v62, 16, v51
	v_and_b32_e32 v63, 0xffff0000, v51
	v_pk_mul_f32 v[56:57], v[80:81], v[56:57] op_sel_hi:[0,1]
	v_pk_mul_f32 v[58:59], v[80:81], v[58:59] op_sel_hi:[0,1]
	v_pk_mul_f32 v[60:61], v[80:81], v[60:61] op_sel_hi:[0,1]
	v_pk_mul_f32 v[62:63], v[80:81], v[62:63] op_sel_hi:[0,1]
	v_pk_mul_f32 v[72:73], v[12:13], v[56:57]
	v_pk_mul_f32 v[74:75], v[14:15], v[58:59]
	v_pk_mul_f32 v[76:77], v[8:9], v[60:61]
	v_pk_mul_f32 v[78:79], v[10:11], v[62:63]
	v_mov_b64_e32 v[82:83], v[52:53]
	global_store_dwordx4 v[82:83], v[64:67], off
	global_store_dwordx4 v[82:83], v[68:71], off offset:16
	global_store_dwordx4 v[82:83], v[72:75], off offset:2048
	global_store_dwordx4 v[82:83], v[76:79], off offset:2064
	s_branch .LBB0_831
	s_branch .LBB0_829
